# peeled K-loop first iteration (no acc zeroing) + attention exp/PV pipelined with spaced MFMAs and 4 sum chains + dropped hazard-free s_nop before DPP in up-proj epilogue
# speedup vs baseline: 1.0279x; 1.0120x over previous
; DI unsigned pk2s(float lo, float hi) { f32x2_t v = {lo, hi}; bf16x2_t q = __builtin_convertvector(v, bf16x2_t); return __builtin_bit_cast(unsigned, q); }
; #define MFMA32(a, b, c) __builtin_amdgcn_mfma_f32_32x32x16_bf16((a), (b), (c), 0, 0, 0)
; DI void attn_unit(const bf16_t* Qb, const bf16_t* Kb, const bf16_t* Vt, bf16_t* MIX, int b, int h, int qb, char* lds, int tid_in) {
;     ...
;             float rs = 0.f;
; #pragma unroll
;             for (int kb = 0; kb < 4; ++kb)
; #pragma unroll
;                 for (int i = 0; i < 16; ++i) { const float e = __builtin_amdgcn_exp2f(p[kb][i]); p[kb][i] = e; rs += e; }
;             l_run += rs;
;             {
;                 bf16x8 vf[2][2];
;                 vf[0][0] = *(const bf16x8*)(vb_ + r * AV_PITCH + (8 * hh) * 2); vf[0][1] = *(const bf16x8*)(vb_ + (32 + r) * AV_PITCH + (8 * hh) * 2);
; #pragma unroll
;                 for (int G = 0; G < 8; ++G) { const int kb = G >> 1, s2 = G & 1;
;                     if (G + 1 < 8) { vf[(G + 1) & 1][0] = *(const bf16x8*)(vb_ + r * AV_PITCH + (16 * (G + 1) + 8 * hh) * 2); vf[(G + 1) & 1][1] = *(const bf16x8*)(vb_ + (32 + r) * AV_PITCH + (16 * (G + 1) + 8 * hh) * 2); }
;                     u32x4 pw; pw.x = pk2s(p[kb][8 * s2], p[kb][8 * s2 + 1]); pw.y = pk2s(p[kb][8 * s2 + 2], p[kb][8 * s2 + 3]); pw.z = pk2s(p[kb][8 * s2 + 4], p[kb][8 * s2 + 5]); pw.w = pk2s(p[kb][8 * s2 + 6], p[kb][8 * s2 + 7]);
;                     const bf16x8 pa = __builtin_bit_cast(bf16x8, pw);
;                     __builtin_amdgcn_sched_barrier(0);
;                     __builtin_amdgcn_s_setprio(1);
;                     o0 = MFMA32(pa, vf[G & 1][0], o0); o1 = MFMA32(pa, vf[G & 1][1], o1);
;                     __builtin_amdgcn_s_setprio(0);
;                     __builtin_amdgcn_sched_barrier(0);
;                 }
.LBB0_467:
	v_add3_u32 v244, s16, v175, v176
	ds_read_b128 v[190:193], v244 offset:24576
	ds_read_b128 v[194:197], v244 offset:33280
	ds_read_b128 v[198:201], v244 offset:24608
	ds_read_b128 v[212:215], v244 offset:33312
	v_exp_f32_e32 v82, v82
	v_exp_f32_e32 v83, v83
	v_exp_f32_e32 v84, v84
	v_exp_f32_e32 v85, v85
	v_exp_f32_e32 v86, v86
	v_exp_f32_e32 v87, v87
	v_exp_f32_e32 v88, v88
	v_exp_f32_e32 v89, v89
	v_exp_f32_e32 v90, v90
	v_mov_b32_e32 v245, v82
	v_exp_f32_e32 v91, v91
	v_mov_b32_e32 v246, v83
	v_exp_f32_e32 v92, v92
	v_mov_b32_e32 v247, v84
	v_exp_f32_e32 v93, v93
	v_mov_b32_e32 v248, v85
	v_exp_f32_e32 v94, v94
	v_add_f32_e32 v245, v86, v245
	v_exp_f32_e32 v95, v95
	v_add_f32_e32 v246, v87, v246
	v_exp_f32_e32 v96, v96
	v_add_f32_e32 v247, v88, v247
	v_exp_f32_e32 v97, v97
	v_add_f32_e32 v248, v89, v248
	v_cvt_pk_bf16_f32 v216, v82, v83
	v_cvt_pk_bf16_f32 v217, v84, v85
	v_cvt_pk_bf16_f32 v218, v86, v87
	v_cvt_pk_bf16_f32 v219, v88, v89
	s_waitcnt lgkmcnt(2)
	s_nop 0
	v_mfma_f32_32x32x16_bf16 v[18:33], v[216:219], v[190:193], v[18:33]
	v_exp_f32_e32 v66, v66
	v_add_f32_e32 v245, v90, v245
	v_exp_f32_e32 v67, v67
	v_add_f32_e32 v246, v91, v246
	v_exp_f32_e32 v68, v68
	v_add_f32_e32 v247, v92, v247
	v_exp_f32_e32 v69, v69
	v_add_f32_e32 v248, v93, v248
	v_mfma_f32_32x32x16_bf16 v[2:17], v[216:219], v[194:197], v[2:17]
	ds_read_b128 v[190:193], v244 offset:24640
	ds_read_b128 v[194:197], v244 offset:33344
	v_exp_f32_e32 v70, v70
	v_add_f32_e32 v245, v94, v245
	v_exp_f32_e32 v71, v71
	v_add_f32_e32 v246, v95, v246
	v_exp_f32_e32 v72, v72
	v_add_f32_e32 v247, v96, v247
	v_exp_f32_e32 v73, v73
	v_add_f32_e32 v248, v97, v248
	v_cvt_pk_bf16_f32 v224, v90, v91
	v_cvt_pk_bf16_f32 v225, v92, v93
	v_cvt_pk_bf16_f32 v226, v94, v95
	v_cvt_pk_bf16_f32 v227, v96, v97
	s_waitcnt lgkmcnt(2)
	s_nop 0
	v_mfma_f32_32x32x16_bf16 v[18:33], v[224:227], v[198:201], v[18:33]
	v_exp_f32_e32 v74, v74
	v_add_f32_e32 v245, v66, v245
	v_exp_f32_e32 v75, v75
	v_add_f32_e32 v246, v67, v246
	v_exp_f32_e32 v76, v76
	v_add_f32_e32 v247, v68, v247
	v_exp_f32_e32 v77, v77
	v_add_f32_e32 v248, v69, v248
	v_mfma_f32_32x32x16_bf16 v[2:17], v[224:227], v[212:215], v[2:17]
	ds_read_b128 v[198:201], v244 offset:24672
	ds_read_b128 v[212:215], v244 offset:33376
	v_exp_f32_e32 v78, v78
	v_add_f32_e32 v245, v70, v245
	v_exp_f32_e32 v79, v79
	v_add_f32_e32 v246, v71, v246
	v_exp_f32_e32 v80, v80
	v_add_f32_e32 v247, v72, v247
	v_exp_f32_e32 v81, v81
	v_add_f32_e32 v248, v73, v248
	v_cvt_pk_bf16_f32 v216, v66, v67
	v_cvt_pk_bf16_f32 v217, v68, v69
	v_cvt_pk_bf16_f32 v218, v70, v71
	v_cvt_pk_bf16_f32 v219, v72, v73
	s_waitcnt lgkmcnt(2)
	s_nop 0
	v_mfma_f32_32x32x16_bf16 v[18:33], v[216:219], v[190:193], v[18:33]
	v_exp_f32_e32 v50, v50
	v_add_f32_e32 v245, v74, v245
	v_exp_f32_e32 v51, v51
	v_add_f32_e32 v246, v75, v246
	v_exp_f32_e32 v52, v52
	v_add_f32_e32 v247, v76, v247
	v_exp_f32_e32 v53, v53
	v_add_f32_e32 v248, v77, v248
	v_mfma_f32_32x32x16_bf16 v[2:17], v[216:219], v[194:197], v[2:17]
	ds_read_b128 v[190:193], v244 offset:24704
	ds_read_b128 v[194:197], v244 offset:33408
	v_exp_f32_e32 v54, v54
	v_add_f32_e32 v245, v78, v245
	v_exp_f32_e32 v55, v55
	v_add_f32_e32 v246, v79, v246
	v_exp_f32_e32 v56, v56
	v_add_f32_e32 v247, v80, v247
	v_exp_f32_e32 v57, v57
	v_add_f32_e32 v248, v81, v248
	v_cvt_pk_bf16_f32 v224, v74, v75
	v_cvt_pk_bf16_f32 v225, v76, v77
	v_cvt_pk_bf16_f32 v226, v78, v79
	v_cvt_pk_bf16_f32 v227, v80, v81
	s_waitcnt lgkmcnt(2)
	s_nop 0
	v_mfma_f32_32x32x16_bf16 v[18:33], v[224:227], v[198:201], v[18:33]
	v_exp_f32_e32 v58, v58
	v_add_f32_e32 v245, v50, v245
	v_exp_f32_e32 v59, v59
	v_add_f32_e32 v246, v51, v246
	v_exp_f32_e32 v60, v60
	v_add_f32_e32 v247, v52, v247
	v_exp_f32_e32 v61, v61
	v_add_f32_e32 v248, v53, v248
	v_mfma_f32_32x32x16_bf16 v[2:17], v[224:227], v[212:215], v[2:17]
	ds_read_b128 v[198:201], v244 offset:24736
	ds_read_b128 v[212:215], v244 offset:33440
	v_exp_f32_e32 v62, v62
	v_add_f32_e32 v245, v54, v245
	v_exp_f32_e32 v63, v63
	v_add_f32_e32 v246, v55, v246
	v_exp_f32_e32 v64, v64
	v_add_f32_e32 v247, v56, v247
	v_exp_f32_e32 v65, v65
	v_add_f32_e32 v248, v57, v248
	v_cvt_pk_bf16_f32 v216, v50, v51
	v_cvt_pk_bf16_f32 v217, v52, v53
	v_cvt_pk_bf16_f32 v218, v54, v55
	v_cvt_pk_bf16_f32 v219, v56, v57
	s_waitcnt lgkmcnt(2)
	s_nop 0
	v_mfma_f32_32x32x16_bf16 v[18:33], v[216:219], v[190:193], v[18:33]
	v_exp_f32_e32 v34, v34
	v_add_f32_e32 v245, v58, v245
	v_exp_f32_e32 v35, v35
	v_add_f32_e32 v246, v59, v246
	v_exp_f32_e32 v36, v36
	v_add_f32_e32 v247, v60, v247
	v_exp_f32_e32 v37, v37
	v_add_f32_e32 v248, v61, v248
	v_mfma_f32_32x32x16_bf16 v[2:17], v[216:219], v[194:197], v[2:17]
	ds_read_b128 v[190:193], v244 offset:24768
	ds_read_b128 v[194:197], v244 offset:33472
	v_exp_f32_e32 v38, v38
	v_add_f32_e32 v245, v62, v245
	v_exp_f32_e32 v39, v39
	v_add_f32_e32 v246, v63, v246
	v_exp_f32_e32 v40, v40
	v_add_f32_e32 v247, v64, v247
	v_exp_f32_e32 v41, v41
	v_add_f32_e32 v248, v65, v248
	v_cvt_pk_bf16_f32 v224, v58, v59
	v_cvt_pk_bf16_f32 v225, v60, v61
	v_cvt_pk_bf16_f32 v226, v62, v63
	v_cvt_pk_bf16_f32 v227, v64, v65
	s_waitcnt lgkmcnt(2)
	s_nop 0
	v_mfma_f32_32x32x16_bf16 v[18:33], v[224:227], v[198:201], v[18:33]
	v_exp_f32_e32 v42, v42
	v_add_f32_e32 v245, v34, v245
	v_exp_f32_e32 v43, v43
	v_add_f32_e32 v246, v35, v246
	v_exp_f32_e32 v44, v44
	v_add_f32_e32 v247, v36, v247
	v_exp_f32_e32 v45, v45
	v_add_f32_e32 v248, v37, v248
	v_mfma_f32_32x32x16_bf16 v[2:17], v[224:227], v[212:215], v[2:17]
	ds_read_b128 v[198:201], v244 offset:24800
	ds_read_b128 v[212:215], v244 offset:33504
	v_exp_f32_e32 v46, v46
	v_add_f32_e32 v245, v38, v245
	v_exp_f32_e32 v47, v47
	v_add_f32_e32 v246, v39, v246
	v_exp_f32_e32 v48, v48
	v_add_f32_e32 v247, v40, v247
	v_exp_f32_e32 v49, v49
	v_add_f32_e32 v248, v41, v248
	v_cvt_pk_bf16_f32 v216, v34, v35
	v_cvt_pk_bf16_f32 v217, v36, v37
	v_cvt_pk_bf16_f32 v218, v38, v39
	v_cvt_pk_bf16_f32 v219, v40, v41
	s_waitcnt lgkmcnt(2)
	s_nop 0
	v_mfma_f32_32x32x16_bf16 v[18:33], v[216:219], v[190:193], v[18:33]
	v_mfma_f32_32x32x16_bf16 v[2:17], v[216:219], v[194:197], v[2:17]
	v_cvt_pk_bf16_f32 v224, v42, v43
	v_cvt_pk_bf16_f32 v225, v44, v45
	v_cvt_pk_bf16_f32 v226, v46, v47
	v_cvt_pk_bf16_f32 v227, v48, v49
	s_waitcnt lgkmcnt(0)
	s_nop 0
	v_mfma_f32_32x32x16_bf16 v[18:33], v[224:227], v[198:201], v[18:33]
	v_mfma_f32_32x32x16_bf16 v[2:17], v[224:227], v[212:215], v[2:17]
	s_nop 0
	v_add_f32_e32 v245, v42, v245
	v_add_f32_e32 v246, v43, v246
	v_add_f32_e32 v247, v44, v247
	v_add_f32_e32 v248, v45, v248
	v_add_f32_e32 v245, v46, v245
	v_add_f32_e32 v246, v47, v246
	v_add_f32_e32 v247, v48, v247
	v_add_f32_e32 v248, v49, v248
	v_add_f32_e32 v245, v245, v246
	v_add_f32_e32 v247, v247, v248
	v_add_f32_e32 v245, v245, v247
	s_nop 0
	v_add_f32_e32 v0, v0, v245

; __device__ __forceinline__ unsigned cvt_pk_bf16(float lo, float hi) { unsigned r; asm volatile("v_cvt_pk_bf16_f32 %0, %1, %2" : "=v"(r) : "v"(lo), "v"(hi)); return r; }
; DI float dpp_ror1(float x) { float r; asm volatile("s_nop 1\n\tv_mov_b32_dpp %0, %1 row_ror:1 row_mask:0xf bank_mask:0xf" : "=v"(r) : "v"(x)); return r; }
; DI float dpp_ror2(float x) { float r; asm volatile("s_nop 1\n\tv_mov_b32_dpp %0, %1 row_ror:2 row_mask:0xf bank_mask:0xf" : "=v"(r) : "v"(x)); return r; }
;     __device__ __forceinline__ void operator()(const f32x4 (&acc)[2][2][4][2], const Unit& u, int wr, int wc, int fr_in, int fq_in) const {
;     ...
;                 for (int m = 0; m < 4; ++m) {
;                     f32x4 uu[2];
; #pragma unroll
;                     for (int bj = 0; bj < 2; ++bj) {
;                         const f32x4 cur = acc[ai][bj][m][n];
;                         f32x4 r1, r2;
; #pragma unroll
;                         for (int j = 0; j < 4; ++j) { r1[j] = dpp_ror1(cur[j]); r2[j] = dpp_ror2(cur[j]); }
;                         const f32x4 p1 = (fr >= 1) ? r1 : r1p[bj], p2 = (fr >= 2) ? r2 : r2p[bj];
;                         uu[bj] = w0[bj] * p2 + w1[bj] * p1 + w2[bj] * cur + bb[bj];
;                         r1p[bj] = r1; r2p[bj] = r2;
;                     }
;                     const int row = row0 + ai * HALF + m * 16;
;                     float a[4];
; #pragma unroll
;                     for (int j = 0; j < 4; ++j) { const float g = uu[0][j]; a[j] = g * __builtin_amdgcn_rcpf(1.f + __expf(-g)) * uu[1][j]; }
;                     u32x2 w; w.x = cvt_pk_bf16(a[0], a[1]); w.y = cvt_pk_bf16(a[2], a[3]);
;                     *(u32x2*)(ACT + (size_t)row * FFN + u.pn * HALF + wc * 32 + 8 * fq + 4 * n) = w;
.LBB0_720:
	s_or_b64 exec, exec, s[42:43]
	v_cmp_eq_u32_e32 vcc, 0, v217
	v_cmp_lt_u32_e64 s[42:43], 1, v217
	v_mov_b32_dpp v223, v126 row_ror:1 row_mask:0xf bank_mask:0xf
	v_mov_b32_dpp v224, v126 row_ror:2 row_mask:0xf bank_mask:0xf
	v_mov_b32_dpp v225, v127 row_ror:1 row_mask:0xf bank_mask:0xf
	v_mov_b32_dpp v226, v127 row_ror:2 row_mask:0xf bank_mask:0xf
	s_waitcnt lgkmcnt(0)
	v_cndmask_b32_e32 v175, v167, v175, vcc
	v_cndmask_b32_e32 v218, v166, v174, vcc
	v_cndmask_b32_e32 v177, v169, v177, vcc
	v_cndmask_b32_e32 v176, v168, v176, vcc
	v_cndmask_b32_e32 v221, v165, v173, vcc
	v_cndmask_b32_e32 v222, v164, v172, vcc
	v_cndmask_b32_e64 v172, v218, v224, s[42:43]
	v_cndmask_b32_e64 v173, v175, v226, s[42:43]
	s_lshl_b32 s2, s50, 8
	v_cndmask_b32_e32 v219, v163, v171, vcc
	v_cndmask_b32_e32 v220, v162, v170, vcc
	v_mov_b32_dpp v227, v128 row_ror:1 row_mask:0xf bank_mask:0xf
	v_mov_b32_dpp v228, v128 row_ror:2 row_mask:0xf bank_mask:0xf
	v_mov_b32_dpp v229, v129 row_ror:1 row_mask:0xf bank_mask:0xf
	v_mov_b32_dpp v230, v129 row_ror:2 row_mask:0xf bank_mask:0xf
	v_cndmask_b32_e32 v166, v223, v166, vcc
	v_cndmask_b32_e32 v167, v225, v167, vcc
	v_cndmask_b32_e64 v170, v176, v228, s[42:43]
	v_cndmask_b32_e64 v171, v177, v230, s[42:43]
	v_pk_mul_f32 v[172:173], v[150:151], v[172:173]
	s_add_i32 s2, s2, s67
	v_cndmask_b32_e32 v168, v227, v168, vcc
	v_cndmask_b32_e32 v169, v229, v169, vcc
	v_pk_mul_f32 v[170:171], v[152:153], v[170:171]
	v_pk_fma_f32 v[166:167], v[146:147], v[166:167], v[172:173]
	v_or_b32_e32 v174, s2, v217
	v_pk_fma_f32 v[168:169], v[148:149], v[168:169], v[170:171]
	v_pk_fma_f32 v[126:127], v[126:127], v[138:139], v[166:167]
	v_mov_b32_dpp v170, v122 row_ror:1 row_mask:0xf bank_mask:0xf
	v_mov_b32_dpp v171, v122 row_ror:2 row_mask:0xf bank_mask:0xf
	v_mov_b32_dpp v172, v123 row_ror:1 row_mask:0xf bank_mask:0xf
	v_mov_b32_dpp v173, v123 row_ror:2 row_mask:0xf bank_mask:0xf
	v_mov_b32_dpp v175, v124 row_ror:1 row_mask:0xf bank_mask:0xf
	v_mov_b32_dpp v176, v124 row_ror:2 row_mask:0xf bank_mask:0xf
	v_mov_b32_dpp v177, v125 row_ror:1 row_mask:0xf bank_mask:0xf
	v_mov_b32_dpp v217, v125 row_ror:2 row_mask:0xf bank_mask:0xf
	s_nop 0
	v_pk_add_f32 v[126:127], v[134:135], v[126:127]
	v_cndmask_b32_e64 v166, v222, v176, s[42:43]
	v_cndmask_b32_e64 v167, v221, v217, s[42:43]
	v_cndmask_b32_e32 v164, v175, v164, vcc
	v_cndmask_b32_e32 v165, v177, v165, vcc
	v_pk_mul_f32 v[166:167], v[160:161], v[166:167]
	v_pk_fma_f32 v[128:129], v[128:129], v[140:141], v[168:169]
	v_pk_fma_f32 v[164:165], v[156:157], v[164:165], v[166:167]
	v_mul_f32_e32 v166, 0xbfb8aa3b, v126
	v_exp_f32_e32 v166, v166
	v_cndmask_b32_e64 v168, v220, v171, s[42:43]
	v_cndmask_b32_e64 v169, v219, v173, s[42:43]
	v_cndmask_b32_e32 v162, v170, v162, vcc
	v_cndmask_b32_e32 v163, v172, v163, vcc
	v_pk_mul_f32 v[168:169], v[158:159], v[168:169]
	v_pk_add_f32 v[128:129], v[136:137], v[128:129]
	v_pk_fma_f32 v[162:163], v[154:155], v[162:163], v[168:169]
	v_pk_fma_f32 v[124:125], v[124:125], v[144:145], v[164:165]
	v_pk_fma_f32 v[122:123], v[122:123], v[142:143], v[162:163]
	v_add_f32_e32 v162, 1.0, v166
	v_rcp_f32_e32 v162, v162
	v_mul_f32_e32 v163, 0xbfb8aa3b, v127
	v_exp_f32_e32 v163, v163
	v_pk_add_f32 v[122:123], v[130:131], v[122:123]
	v_mul_f32_e32 v126, v126, v162
	v_mul_f32_e32 v122, v126, v122
	v_add_f32_e32 v126, 1.0, v163
	v_mul_f32_e32 v162, 0xbfb8aa3b, v128
	v_rcp_f32_e32 v126, v126
	v_exp_f32_e32 v162, v162
	v_mul_f32_e32 v163, 0xbfb8aa3b, v129
	v_exp_f32_e32 v163, v163
	v_mul_f32_e32 v126, v127, v126
	v_add_f32_e32 v127, 1.0, v162
	v_rcp_f32_e32 v127, v127
	v_add_f32_e32 v162, 1.0, v163
	v_rcp_f32_e32 v162, v162
	v_pk_add_f32 v[124:125], v[132:133], v[124:125]
	v_mul_f32_e32 v123, v126, v123
	v_mul_f32_e32 v126, v128, v127
	v_readlane_b32 s8, v240, 27
	s_lshl_b32 s46, s51, 7
	v_mul_f32_e32 v126, v126, v124
	v_mul_f32_e32 v124, v129, v162
	v_readlane_b32 s9, v240, 28
	s_ashr_i32 s47, s46, 31
	v_mul_f32_e32 v125, v124, v125
	v_cvt_pk_bf16_f32 v124, v122, v123
	v_mov_b64_e32 v[122:123], s[8:9]
	v_cvt_pk_bf16_f32 v125, v126, v125
	v_mad_i64_i32 v[126:127], s[22:23], v174, s25, v[122:123]
	s_lshl_b64 s[46:47], s[46:47], 1
	v_lshl_add_u64 v[126:127], v[126:127], 0, s[46:47]
	s_lshl_b32 s62, s31, 1
	v_lshl_add_u64 v[126:127], v[126:127], 0, s[62:63]
	v_lshlrev_b64 v[162:163], 1, v[200:201]
	v_lshl_add_u64 v[164:165], v[126:127], 0, v[162:163]
	global_store_dwordx2 v[164:165], v[124:125], off
	v_mov_b32_dpp v168, v118 row_ror:1 row_mask:0xf bank_mask:0xf
	v_mov_b32_dpp v169, v118 row_ror:2 row_mask:0xf bank_mask:0xf
	v_mov_b32_dpp v200, v119 row_ror:1 row_mask:0xf bank_mask:0xf
	v_mov_b32_dpp v201, v119 row_ror:2 row_mask:0xf bank_mask:0xf
	v_mov_b32_dpp v218, v120 row_ror:1 row_mask:0xf bank_mask:0xf
	v_mov_b32_dpp v219, v120 row_ror:2 row_mask:0xf bank_mask:0xf
	v_mov_b32_dpp v220, v121 row_ror:1 row_mask:0xf bank_mask:0xf
	s_nop 0
	v_cndmask_b32_e64 v166, v224, v169, s[42:43]
	v_cndmask_b32_e64 v167, v226, v201, s[42:43]
	v_mov_b32_dpp v221, v121 row_ror:2 row_mask:0xf bank_mask:0xf
	v_cndmask_b32_e32 v124, v168, v223, vcc
	v_cndmask_b32_e32 v125, v200, v225, vcc
	v_cndmask_b32_e64 v128, v228, v219, s[42:43]
	v_cndmask_b32_e64 v129, v230, v221, s[42:43]
	v_pk_mul_f32 v[166:167], v[150:151], v[166:167]
	v_cndmask_b32_e32 v126, v218, v227, vcc
	v_cndmask_b32_e32 v127, v220, v229, vcc
	v_pk_mul_f32 v[128:129], v[152:153], v[128:129]
	v_pk_fma_f32 v[124:125], v[146:147], v[124:125], v[166:167]
	v_pk_fma_f32 v[126:127], v[148:149], v[126:127], v[128:129]
	v_pk_fma_f32 v[118:119], v[118:119], v[138:139], v[124:125]
	v_mov_b32_dpp v222, v114 row_ror:1 row_mask:0xf bank_mask:0xf
; __device__ __forceinline__ unsigned cvt_pk_bf16(float lo, float hi) { unsigned r; asm volatile("v_cvt_pk_bf16_f32 %0, %1, %2" : "=v"(r) : "v"(lo), "v"(hi)); return r; }
; DI float dpp_ror1(float x) { float r; asm volatile("s_nop 1\n\tv_mov_b32_dpp %0, %1 row_ror:1 row_mask:0xf bank_mask:0xf" : "=v"(r) : "v"(x)); return r; }
; DI float dpp_ror2(float x) { float r; asm volatile("s_nop 1\n\tv_mov_b32_dpp %0, %1 row_ror:2 row_mask:0xf bank_mask:0xf" : "=v"(r) : "v"(x)); return r; }
;     __device__ __forceinline__ void operator()(const f32x4 (&acc)[2][2][4][2], const Unit& u, int wr, int wc, int fr_in, int fq_in) const {
;     ...
;                 for (int m = 0; m < 4; ++m) {
;                     f32x4 uu[2];
; #pragma unroll
;                     for (int bj = 0; bj < 2; ++bj) {
;                         const f32x4 cur = acc[ai][bj][m][n];
;                         f32x4 r1, r2;
; #pragma unroll
;                         for (int j = 0; j < 4; ++j) { r1[j] = dpp_ror1(cur[j]); r2[j] = dpp_ror2(cur[j]); }
;                         const f32x4 p1 = (fr >= 1) ? r1 : r1p[bj], p2 = (fr >= 2) ? r2 : r2p[bj];
;                         uu[bj] = w0[bj] * p2 + w1[bj] * p1 + w2[bj] * cur + bb[bj];
;                         r1p[bj] = r1; r2p[bj] = r2;
;                     }
;                     const int row = row0 + ai * HALF + m * 16;
;                     float a[4];
; #pragma unroll
;                     for (int j = 0; j < 4; ++j) { const float g = uu[0][j]; a[j] = g * __builtin_amdgcn_rcpf(1.f + __expf(-g)) * uu[1][j]; }
;                     u32x2 w; w.x = cvt_pk_bf16(a[0], a[1]); w.y = cvt_pk_bf16(a[2], a[3]);
;                     *(u32x2*)(ACT + (size_t)row * FFN + u.pn * HALF + wc * 32 + 8 * fq + 4 * n) = w;
	v_mov_b32_dpp v223, v114 row_ror:2 row_mask:0xf bank_mask:0xf
	v_mov_b32_dpp v224, v115 row_ror:1 row_mask:0xf bank_mask:0xf
	v_mov_b32_dpp v225, v115 row_ror:2 row_mask:0xf bank_mask:0xf
	v_mov_b32_dpp v226, v116 row_ror:1 row_mask:0xf bank_mask:0xf
	v_mov_b32_dpp v227, v116 row_ror:2 row_mask:0xf bank_mask:0xf
	v_mov_b32_dpp v228, v117 row_ror:1 row_mask:0xf bank_mask:0xf
	v_mov_b32_dpp v229, v117 row_ror:2 row_mask:0xf bank_mask:0xf
	v_pk_fma_f32 v[120:121], v[120:121], v[140:141], v[126:127]
	v_cndmask_b32_e64 v128, v176, v227, s[42:43]
	v_cndmask_b32_e64 v129, v217, v229, s[42:43]
	v_pk_add_f32 v[118:119], v[134:135], v[118:119]
	v_cndmask_b32_e32 v126, v226, v175, vcc
	v_cndmask_b32_e32 v127, v228, v177, vcc
	v_pk_mul_f32 v[128:129], v[160:161], v[128:129]
	v_cndmask_b32_e64 v166, v171, v223, s[42:43]
	v_pk_fma_f32 v[126:127], v[156:157], v[126:127], v[128:129]
	v_mul_f32_e32 v128, 0xbfb8aa3b, v118
	v_exp_f32_e32 v128, v128
	v_cndmask_b32_e64 v167, v173, v225, s[42:43]
	v_cndmask_b32_e32 v124, v222, v170, vcc
	v_cndmask_b32_e32 v125, v224, v172, vcc
	v_pk_mul_f32 v[166:167], v[158:159], v[166:167]
	v_pk_add_f32 v[120:121], v[136:137], v[120:121]
	v_pk_fma_f32 v[124:125], v[154:155], v[124:125], v[166:167]
	v_pk_fma_f32 v[116:117], v[116:117], v[144:145], v[126:127]
	v_pk_fma_f32 v[114:115], v[114:115], v[142:143], v[124:125]
	v_add_f32_e32 v124, 1.0, v128
	v_rcp_f32_e32 v124, v124
	v_mul_f32_e32 v125, 0xbfb8aa3b, v119
	v_exp_f32_e32 v125, v125
	v_pk_add_f32 v[114:115], v[130:131], v[114:115]
	v_mul_f32_e32 v118, v118, v124
	v_mul_f32_e32 v114, v118, v114
	v_add_f32_e32 v118, 1.0, v125
	v_mul_f32_e32 v124, 0xbfb8aa3b, v120
	v_rcp_f32_e32 v118, v118
	v_exp_f32_e32 v124, v124
	v_mul_f32_e32 v125, 0xbfb8aa3b, v121
	v_exp_f32_e32 v125, v125
	v_mul_f32_e32 v118, v119, v118
	v_add_f32_e32 v119, 1.0, v124
	v_rcp_f32_e32 v119, v119
	v_add_f32_e32 v124, 1.0, v125
	v_rcp_f32_e32 v124, v124
	v_pk_add_f32 v[116:117], v[132:133], v[116:117]
	v_mul_f32_e32 v115, v118, v115
	v_mul_f32_e32 v118, v120, v119
	v_mul_f32_e32 v116, v118, v116
	v_mul_f32_e32 v118, v121, v124
	v_mul_f32_e32 v117, v118, v117
	v_or_b32_e32 v118, 16, v174
	v_cvt_pk_bf16_f32 v114, v114, v115
	v_cvt_pk_bf16_f32 v115, v116, v117
	v_mad_i64_i32 v[116:117], s[22:23], v118, s25, v[122:123]
	v_lshl_add_u64 v[116:117], v[116:117], 0, s[46:47]
	v_lshl_add_u64 v[116:117], v[116:117], 0, s[62:63]
	v_lshl_add_u64 v[166:167], v[116:117], 0, v[162:163]
	global_store_dwordx2 v[166:167], v[114:115], off
	v_mov_b32_dpp v124, v110 row_ror:1 row_mask:0xf bank_mask:0xf
	v_mov_b32_dpp v125, v110 row_ror:2 row_mask:0xf bank_mask:0xf
	v_mov_b32_dpp v126, v111 row_ror:1 row_mask:0xf bank_mask:0xf
	v_mov_b32_dpp v127, v111 row_ror:2 row_mask:0xf bank_mask:0xf
	v_mov_b32_dpp v128, v112 row_ror:1 row_mask:0xf bank_mask:0xf
	v_mov_b32_dpp v129, v112 row_ror:2 row_mask:0xf bank_mask:0xf
	v_mov_b32_dpp v170, v113 row_ror:1 row_mask:0xf bank_mask:0xf
	s_nop 0
	v_cndmask_b32_e64 v120, v169, v125, s[42:43]
	v_cndmask_b32_e64 v121, v201, v127, s[42:43]
	v_mov_b32_dpp v171, v113 row_ror:2 row_mask:0xf bank_mask:0xf
	v_cndmask_b32_e32 v114, v124, v168, vcc
	v_cndmask_b32_e32 v115, v126, v200, vcc
	v_cndmask_b32_e64 v118, v219, v129, s[42:43]
	v_cndmask_b32_e64 v119, v221, v171, s[42:43]
	v_pk_mul_f32 v[120:121], v[150:151], v[120:121]
	v_cndmask_b32_e32 v116, v128, v218, vcc
	v_cndmask_b32_e32 v117, v170, v220, vcc
	v_pk_mul_f32 v[118:119], v[152:153], v[118:119]
	v_pk_fma_f32 v[114:115], v[146:147], v[114:115], v[120:121]
	v_pk_fma_f32 v[116:117], v[148:149], v[116:117], v[118:119]
	v_pk_fma_f32 v[110:111], v[110:111], v[138:139], v[114:115]
	v_mov_b32_dpp v172, v106 row_ror:1 row_mask:0xf bank_mask:0xf
	v_mov_b32_dpp v173, v106 row_ror:2 row_mask:0xf bank_mask:0xf
	v_mov_b32_dpp v175, v107 row_ror:1 row_mask:0xf bank_mask:0xf
	v_mov_b32_dpp v176, v107 row_ror:2 row_mask:0xf bank_mask:0xf
	v_mov_b32_dpp v177, v108 row_ror:1 row_mask:0xf bank_mask:0xf
	v_mov_b32_dpp v200, v108 row_ror:2 row_mask:0xf bank_mask:0xf
	v_mov_b32_dpp v201, v109 row_ror:1 row_mask:0xf bank_mask:0xf
	v_mov_b32_dpp v217, v109 row_ror:2 row_mask:0xf bank_mask:0xf
	v_pk_fma_f32 v[112:113], v[112:113], v[140:141], v[116:117]
	v_cndmask_b32_e64 v118, v227, v200, s[42:43]
	v_cndmask_b32_e64 v119, v229, v217, s[42:43]
	v_pk_add_f32 v[110:111], v[134:135], v[110:111]
	v_cndmask_b32_e32 v116, v177, v226, vcc
	v_cndmask_b32_e32 v117, v201, v228, vcc
	v_pk_mul_f32 v[118:119], v[160:161], v[118:119]
	v_cndmask_b32_e64 v120, v223, v173, s[42:43]
	v_pk_fma_f32 v[116:117], v[156:157], v[116:117], v[118:119]
	v_mul_f32_e32 v118, 0xbfb8aa3b, v110
	v_exp_f32_e32 v118, v118
	v_cndmask_b32_e64 v121, v225, v176, s[42:43]
	v_cndmask_b32_e32 v114, v172, v222, vcc
	v_cndmask_b32_e32 v115, v175, v224, vcc
	v_pk_mul_f32 v[120:121], v[158:159], v[120:121]
	v_pk_add_f32 v[112:113], v[136:137], v[112:113]
	v_pk_fma_f32 v[114:115], v[154:155], v[114:115], v[120:121]
	v_pk_fma_f32 v[108:109], v[108:109], v[144:145], v[116:117]
	v_pk_fma_f32 v[106:107], v[106:107], v[142:143], v[114:115]
	v_add_f32_e32 v114, 1.0, v118
	v_rcp_f32_e32 v114, v114
	v_mul_f32_e32 v115, 0xbfb8aa3b, v111
	v_exp_f32_e32 v115, v115
	v_pk_add_f32 v[106:107], v[130:131], v[106:107]
	v_mul_f32_e32 v110, v110, v114
; DI float dpp_ror1(float x) { float r; asm volatile("s_nop 1\n\tv_mov_b32_dpp %0, %1 row_ror:1 row_mask:0xf bank_mask:0xf" : "=v"(r) : "v"(x)); return r; }
;     __device__ __forceinline__ void operator()(const f32x4 (&acc)[2][2][4][2], const Unit& u, int wr, int wc, int fr_in, int fq_in) const {
;     ...
; #pragma unroll
;                 for (int bj = 0; bj < 2; ++bj) {
;                     const int tcol = bj * HALF + wc * 32 + 8 * fq + 4 * n;
;                     w0[bj] = *(const f32x4*)(cwl + eo + tcol); w1[bj] = *(const f32x4*)(cwl + eo + 256 + tcol); w2[bj] = *(const f32x4*)(cwl + eo + 512 + tcol); bb[bj] = *(const f32x4*)(cwl + eo + 768 + tcol);
;                     f32x4 E0 = (f32x4){0.f, 0.f, 0.f, 0.f}, E1 = E0;
;                     if (fr < 2) {
;                         if (wr == 1 || ai == 1) {
;                             const int sai = (wr == 1) ? ai : 0, swr = (wr == 1) ? 0 : 1;
;                             const int e = (((((sai * 2 + swr) * 4 + wc) * 2 + bj) * 2 + n) * 4 + fq) * 2;
;                             E0 = ex[e]; E1 = ex[e + 1];
;                         }
;                     }
;                     r1p[bj] = E1; r2p[bj] = (fr == 0) ? E0 : E1;
;                 }
; #pragma unroll
;                 for (int m = 0; m < 4; ++m) {
;                     f32x4 uu[2];
; #pragma unroll
;                     for (int bj = 0; bj < 2; ++bj) {
;                         const f32x4 cur = acc[ai][bj][m][n];
;                         f32x4 r1, r2;
; #pragma unroll
;                         for (int j = 0; j < 4; ++j) { r1[j] = dpp_ror1(cur[j]); r2[j] = dpp_ror2(cur[j]); }
;                         const f32x4 p1 = (fr >= 1) ? r1 : r1p[bj], p2 = (fr >= 2) ? r2 : r2p[bj];
;                         uu[bj] = w0[bj] * p2 + w1[bj] * p1 + w2[bj] * cur + bb[bj];
;                         r1p[bj] = r1; r2p[bj] = r2;
;                     }
;                     const int row = row0 + ai * HALF + m * 16;
;                     float a[4];
; #pragma unroll
;                     for (int j = 0; j < 4; ++j) { const float g = uu[0][j]; a[j] = g * __builtin_amdgcn_rcpf(1.f + __expf(-g)) * uu[1][j]; }
;                     u32x2 w; w.x = cvt_pk_bf16(a[0], a[1]); w.y = cvt_pk_bf16(a[2], a[3]);
;                     *(u32x2*)(ACT + (size_t)row * FFN + u.pn * HALF + wc * 32 + 8 * fq + 4 * n) = w;
	v_mul_f32_e32 v106, v110, v106
	v_add_f32_e32 v110, 1.0, v115
	v_mul_f32_e32 v114, 0xbfb8aa3b, v112
	v_rcp_f32_e32 v110, v110
	v_exp_f32_e32 v114, v114
	v_mul_f32_e32 v115, 0xbfb8aa3b, v113
	v_exp_f32_e32 v115, v115
	v_mul_f32_e32 v110, v111, v110
	v_add_f32_e32 v111, 1.0, v114
	v_rcp_f32_e32 v111, v111
	v_add_f32_e32 v114, 1.0, v115
	v_rcp_f32_e32 v114, v114
	v_pk_add_f32 v[108:109], v[132:133], v[108:109]
	v_mul_f32_e32 v107, v110, v107
	v_mul_f32_e32 v110, v112, v111
	v_mul_f32_e32 v108, v110, v108
	v_mul_f32_e32 v110, v113, v114
	v_mul_f32_e32 v109, v110, v109
	v_or_b32_e32 v110, 32, v174
	v_cvt_pk_bf16_f32 v106, v106, v107
	v_cvt_pk_bf16_f32 v107, v108, v109
	v_mad_i64_i32 v[108:109], s[22:23], v110, s25, v[122:123]
	v_lshl_add_u64 v[108:109], v[108:109], 0, s[46:47]
	v_lshl_add_u64 v[108:109], v[108:109], 0, s[62:63]
	v_lshl_add_u64 v[168:169], v[108:109], 0, v[162:163]
	global_store_dwordx2 v[168:169], v[106:107], off
	v_mov_b32_dpp v106, v102 row_ror:1 row_mask:0xf bank_mask:0xf
	v_mov_b32_dpp v112, v102 row_ror:2 row_mask:0xf bank_mask:0xf
	v_mov_b32_dpp v107, v103 row_ror:1 row_mask:0xf bank_mask:0xf
	v_mov_b32_dpp v113, v103 row_ror:2 row_mask:0xf bank_mask:0xf
	v_mov_b32_dpp v108, v104 row_ror:1 row_mask:0xf bank_mask:0xf
	v_mov_b32_dpp v110, v104 row_ror:2 row_mask:0xf bank_mask:0xf
	v_mov_b32_dpp v109, v105 row_ror:1 row_mask:0xf bank_mask:0xf
	v_mov_b32_dpp v111, v105 row_ror:2 row_mask:0xf bank_mask:0xf
	s_nop 0
	v_cndmask_b32_e64 v112, v125, v112, s[42:43]
	v_cndmask_b32_e64 v110, v129, v110, s[42:43]
	v_cndmask_b32_e64 v111, v171, v111, s[42:43]
	v_cndmask_b32_e64 v113, v127, v113, s[42:43]
	v_cndmask_b32_e32 v106, v106, v124, vcc
	v_cndmask_b32_e32 v107, v107, v126, vcc
	v_cndmask_b32_e32 v108, v108, v128, vcc
	v_cndmask_b32_e32 v109, v109, v170, vcc
	v_pk_mul_f32 v[112:113], v[150:151], v[112:113]
	v_pk_mul_f32 v[110:111], v[152:153], v[110:111]
	v_pk_fma_f32 v[106:107], v[146:147], v[106:107], v[112:113]
	v_pk_fma_f32 v[108:109], v[148:149], v[108:109], v[110:111]
	v_pk_fma_f32 v[102:103], v[102:103], v[138:139], v[106:107]
	v_pk_fma_f32 v[104:105], v[104:105], v[140:141], v[108:109]
	v_mov_b32_dpp v106, v98 row_ror:1 row_mask:0xf bank_mask:0xf
	v_mov_b32_dpp v112, v98 row_ror:2 row_mask:0xf bank_mask:0xf
	v_mov_b32_dpp v107, v99 row_ror:1 row_mask:0xf bank_mask:0xf
	v_mov_b32_dpp v113, v99 row_ror:2 row_mask:0xf bank_mask:0xf
	v_mov_b32_dpp v108, v100 row_ror:1 row_mask:0xf bank_mask:0xf
	v_mov_b32_dpp v110, v100 row_ror:2 row_mask:0xf bank_mask:0xf
	v_mov_b32_dpp v109, v101 row_ror:1 row_mask:0xf bank_mask:0xf
	v_mov_b32_dpp v111, v101 row_ror:2 row_mask:0xf bank_mask:0xf
	v_pk_add_f32 v[102:103], v[134:135], v[102:103]
	v_cndmask_b32_e64 v110, v200, v110, s[42:43]
	v_cndmask_b32_e64 v111, v217, v111, s[42:43]
	v_cndmask_b32_e32 v108, v108, v177, vcc
	v_cndmask_b32_e32 v109, v109, v201, vcc
	v_pk_mul_f32 v[110:111], v[160:161], v[110:111]
	v_cndmask_b32_e64 v112, v173, v112, s[42:43]
	v_pk_fma_f32 v[108:109], v[156:157], v[108:109], v[110:111]
	v_mul_f32_e32 v110, 0xbfb8aa3b, v102
	v_exp_f32_e32 v110, v110
	v_cndmask_b32_e64 v113, v176, v113, s[42:43]
	v_cndmask_b32_e32 v106, v106, v172, vcc
	v_cndmask_b32_e32 v107, v107, v175, vcc
	v_pk_mul_f32 v[112:113], v[158:159], v[112:113]
	v_pk_add_f32 v[104:105], v[136:137], v[104:105]
	v_pk_fma_f32 v[106:107], v[154:155], v[106:107], v[112:113]
	v_pk_fma_f32 v[100:101], v[100:101], v[144:145], v[108:109]
	v_pk_fma_f32 v[98:99], v[98:99], v[142:143], v[106:107]
	v_add_f32_e32 v106, 1.0, v110
	v_rcp_f32_e32 v106, v106
	v_mul_f32_e32 v107, 0xbfb8aa3b, v103
	v_exp_f32_e32 v107, v107
	v_pk_add_f32 v[98:99], v[130:131], v[98:99]
	v_mul_f32_e32 v102, v102, v106
	v_mul_f32_e32 v98, v102, v98
	v_add_f32_e32 v102, 1.0, v107
	v_mul_f32_e32 v106, 0xbfb8aa3b, v104
	v_rcp_f32_e32 v102, v102
	v_exp_f32_e32 v106, v106
	v_mul_f32_e32 v107, 0xbfb8aa3b, v105
	v_exp_f32_e32 v107, v107
	v_mul_f32_e32 v102, v103, v102
	v_add_f32_e32 v103, 1.0, v106
	v_rcp_f32_e32 v103, v103
	v_add_f32_e32 v106, 1.0, v107
	v_rcp_f32_e32 v106, v106
	v_pk_add_f32 v[100:101], v[132:133], v[100:101]
	v_mul_f32_e32 v99, v102, v99
	v_mul_f32_e32 v102, v104, v103
	v_mul_f32_e32 v100, v102, v100
	v_mul_f32_e32 v102, v105, v106
	v_mul_f32_e32 v101, v102, v101
	v_or_b32_e32 v102, 48, v174
	v_cvt_pk_bf16_f32 v98, v98, v99
	v_cvt_pk_bf16_f32 v99, v100, v101
	v_mad_i64_i32 v[100:101], s[22:23], v102, s25, v[122:123]
	v_lshl_add_u64 v[100:101], v[100:101], 0, s[46:47]
	v_lshl_add_u64 v[100:101], v[100:101], 0, s[62:63]
	v_lshl_add_u64 v[146:147], v[100:101], 0, v[162:163]
	global_store_dwordx2 v[146:147], v[98:99], off
	ds_read_b128 v[118:121], v214 offset:16
	ds_read_b128 v[114:117], v214 offset:1040
	ds_read_b128 v[106:109], v214 offset:2064
	ds_read_b128 v[102:105], v214 offset:3088
	v_add_u32_e32 v98, 4, v216
	v_mov_b32_e32 v138, 0
	v_lshlrev_b32_e32 v148, 5, v98
	v_mov_b32_e32 v142, 0
	v_mov_b32_e32 v143, 0
	v_mov_b32_e32 v144, 0
	v_mov_b32_e32 v145, 0
	v_mov_b32_e32 v134, 0
	v_mov_b32_e32 v135, 0
	v_mov_b32_e32 v136, 0
	v_mov_b32_e32 v137, 0
	s_and_saveexec_b64 s[50:51], s[48:49]
	s_cbranch_execz .LBB0_722
	s_lshl_b32 s2, s96, 4
	v_add3_u32 v98, v213, v148, s2
	ds_read_b128 v[142:145], v98
	ds_read_b128 v[134:137], v98 offset:16

; __device__ __forceinline__ unsigned cvt_pk_bf16(float lo, float hi) { unsigned r; asm volatile("v_cvt_pk_bf16_f32 %0, %1, %2" : "=v"(r) : "v"(lo), "v"(hi)); return r; }
; DI float dpp_ror1(float x) { float r; asm volatile("s_nop 1\n\tv_mov_b32_dpp %0, %1 row_ror:1 row_mask:0xf bank_mask:0xf" : "=v"(r) : "v"(x)); return r; }
; DI float dpp_ror2(float x) { float r; asm volatile("s_nop 1\n\tv_mov_b32_dpp %0, %1 row_ror:2 row_mask:0xf bank_mask:0xf" : "=v"(r) : "v"(x)); return r; }
;     __device__ __forceinline__ void operator()(const f32x4 (&acc)[2][2][4][2], const Unit& u, int wr, int wc, int fr_in, int fq_in) const {
;     ...
;                 for (int m = 0; m < 4; ++m) {
;                     f32x4 uu[2];
; #pragma unroll
;                     for (int bj = 0; bj < 2; ++bj) {
;                         const f32x4 cur = acc[ai][bj][m][n];
;                         f32x4 r1, r2;
; #pragma unroll
;                         for (int j = 0; j < 4; ++j) { r1[j] = dpp_ror1(cur[j]); r2[j] = dpp_ror2(cur[j]); }
;                         const f32x4 p1 = (fr >= 1) ? r1 : r1p[bj], p2 = (fr >= 2) ? r2 : r2p[bj];
;                         uu[bj] = w0[bj] * p2 + w1[bj] * p1 + w2[bj] * cur + bb[bj];
;                         r1p[bj] = r1; r2p[bj] = r2;
;                     }
;                     const int row = row0 + ai * HALF + m * 16;
;                     float a[4];
; #pragma unroll
;                     for (int j = 0; j < 4; ++j) { const float g = uu[0][j]; a[j] = g * __builtin_amdgcn_rcpf(1.f + __expf(-g)) * uu[1][j]; }
;                     u32x2 w; w.x = cvt_pk_bf16(a[0], a[1]); w.y = cvt_pk_bf16(a[2], a[3]);
;                     *(u32x2*)(ACT + (size_t)row * FFN + u.pn * HALF + wc * 32 + 8 * fq + 4 * n) = w;
.LBB0_724:
	s_or_b64 exec, exec, s[50:51]
	s_waitcnt lgkmcnt(0)
	v_cndmask_b32_e32 v143, v135, v143, vcc
	v_cndmask_b32_e32 v142, v134, v142, vcc
	v_cndmask_b32_e32 v145, v137, v145, vcc
	v_cndmask_b32_e32 v144, v136, v144, vcc
	v_cndmask_b32_e32 v151, v133, v141, vcc
	v_cndmask_b32_e32 v152, v132, v140, vcc
	v_mov_b32_dpp v153, v94 row_ror:1 row_mask:0xf bank_mask:0xf
	v_mov_b32_dpp v154, v94 row_ror:2 row_mask:0xf bank_mask:0xf
	v_mov_b32_dpp v155, v95 row_ror:1 row_mask:0xf bank_mask:0xf
	v_mov_b32_dpp v156, v95 row_ror:2 row_mask:0xf bank_mask:0xf
	v_cndmask_b32_e32 v149, v131, v139, vcc
	v_cndmask_b32_e64 v140, v142, v154, s[42:43]
	v_cndmask_b32_e64 v141, v143, v156, s[42:43]
	v_cndmask_b32_e32 v150, v130, v138, vcc
	v_mov_b32_dpp v157, v96 row_ror:1 row_mask:0xf bank_mask:0xf
	v_mov_b32_dpp v158, v96 row_ror:2 row_mask:0xf bank_mask:0xf
	v_mov_b32_dpp v159, v97 row_ror:1 row_mask:0xf bank_mask:0xf
	v_mov_b32_dpp v160, v97 row_ror:2 row_mask:0xf bank_mask:0xf
	v_cndmask_b32_e32 v134, v153, v134, vcc
	v_cndmask_b32_e32 v135, v155, v135, vcc
	v_cndmask_b32_e64 v138, v144, v158, s[42:43]
	v_cndmask_b32_e64 v139, v145, v160, s[42:43]
	v_pk_mul_f32 v[140:141], v[118:119], v[140:141]
	v_cndmask_b32_e32 v136, v157, v136, vcc
	v_cndmask_b32_e32 v137, v159, v137, vcc
	v_pk_mul_f32 v[138:139], v[120:121], v[138:139]
	v_pk_fma_f32 v[134:135], v[114:115], v[134:135], v[140:141]
	v_pk_fma_f32 v[136:137], v[116:117], v[136:137], v[138:139]
	v_pk_fma_f32 v[94:95], v[94:95], v[106:107], v[134:135]
	v_mov_b32_dpp v138, v90 row_ror:1 row_mask:0xf bank_mask:0xf
	v_mov_b32_dpp v139, v90 row_ror:2 row_mask:0xf bank_mask:0xf
	v_mov_b32_dpp v140, v91 row_ror:1 row_mask:0xf bank_mask:0xf
	v_mov_b32_dpp v141, v91 row_ror:2 row_mask:0xf bank_mask:0xf
	v_mov_b32_dpp v142, v92 row_ror:1 row_mask:0xf bank_mask:0xf
	v_mov_b32_dpp v143, v92 row_ror:2 row_mask:0xf bank_mask:0xf
	v_mov_b32_dpp v144, v93 row_ror:1 row_mask:0xf bank_mask:0xf
	v_mov_b32_dpp v145, v93 row_ror:2 row_mask:0xf bank_mask:0xf
	s_nop 0
	v_pk_add_f32 v[94:95], v[102:103], v[94:95]
	v_cndmask_b32_e64 v134, v152, v143, s[42:43]
	v_cndmask_b32_e64 v135, v151, v145, s[42:43]
	v_cndmask_b32_e32 v132, v142, v132, vcc
	v_cndmask_b32_e32 v133, v144, v133, vcc
	v_pk_mul_f32 v[134:135], v[128:129], v[134:135]
	v_pk_fma_f32 v[96:97], v[96:97], v[108:109], v[136:137]
	v_pk_fma_f32 v[132:133], v[124:125], v[132:133], v[134:135]
	v_mul_f32_e32 v134, 0xbfb8aa3b, v94
	v_exp_f32_e32 v134, v134
	v_cndmask_b32_e64 v136, v150, v139, s[42:43]
	v_cndmask_b32_e64 v137, v149, v141, s[42:43]
	v_cndmask_b32_e32 v130, v138, v130, vcc
	v_cndmask_b32_e32 v131, v140, v131, vcc
	v_pk_mul_f32 v[136:137], v[126:127], v[136:137]
	v_pk_add_f32 v[96:97], v[104:105], v[96:97]
	v_pk_fma_f32 v[130:131], v[122:123], v[130:131], v[136:137]
	v_pk_fma_f32 v[92:93], v[92:93], v[112:113], v[132:133]
	v_pk_fma_f32 v[90:91], v[90:91], v[110:111], v[130:131]
	v_add_f32_e32 v130, 1.0, v134
	v_rcp_f32_e32 v130, v130
	v_mul_f32_e32 v131, 0xbfb8aa3b, v95
	v_exp_f32_e32 v131, v131
	v_pk_add_f32 v[90:91], v[98:99], v[90:91]
	v_mul_f32_e32 v94, v94, v130
	v_mul_f32_e32 v90, v94, v90
	v_add_f32_e32 v94, 1.0, v131
	v_mul_f32_e32 v130, 0xbfb8aa3b, v96
	v_rcp_f32_e32 v94, v94
	v_exp_f32_e32 v130, v130
	v_mul_f32_e32 v131, 0xbfb8aa3b, v97
	v_exp_f32_e32 v131, v131
	v_mul_f32_e32 v94, v95, v94
	v_add_f32_e32 v95, 1.0, v130
	v_rcp_f32_e32 v95, v95
	v_add_f32_e32 v130, 1.0, v131
	v_rcp_f32_e32 v130, v130
	v_pk_add_f32 v[92:93], v[100:101], v[92:93]
	v_mul_f32_e32 v91, v94, v91
	v_mul_f32_e32 v94, v96, v95
	v_mul_f32_e32 v92, v94, v92
	v_mul_f32_e32 v94, v97, v130
	v_mul_f32_e32 v93, v94, v93
	v_cvt_pk_bf16_f32 v90, v90, v91
	v_cvt_pk_bf16_f32 v91, v92, v93
	global_store_dwordx2 v[164:165], v[90:91], off offset:8
	v_mov_b32_dpp v130, v86 row_ror:1 row_mask:0xf bank_mask:0xf
	v_mov_b32_dpp v131, v86 row_ror:2 row_mask:0xf bank_mask:0xf
	v_mov_b32_dpp v132, v87 row_ror:1 row_mask:0xf bank_mask:0xf
	v_mov_b32_dpp v133, v87 row_ror:2 row_mask:0xf bank_mask:0xf
	v_mov_b32_dpp v134, v88 row_ror:1 row_mask:0xf bank_mask:0xf
	v_mov_b32_dpp v135, v88 row_ror:2 row_mask:0xf bank_mask:0xf
	v_mov_b32_dpp v136, v89 row_ror:1 row_mask:0xf bank_mask:0xf
	s_nop 0
	v_cndmask_b32_e64 v96, v154, v131, s[42:43]
	v_cndmask_b32_e64 v97, v156, v133, s[42:43]
	v_mov_b32_dpp v137, v89 row_ror:2 row_mask:0xf bank_mask:0xf
	v_cndmask_b32_e32 v90, v130, v153, vcc
	v_cndmask_b32_e32 v91, v132, v155, vcc
	v_cndmask_b32_e64 v94, v158, v135, s[42:43]
	v_cndmask_b32_e64 v95, v160, v137, s[42:43]
	v_pk_mul_f32 v[96:97], v[118:119], v[96:97]
	v_cndmask_b32_e32 v92, v134, v157, vcc
	v_cndmask_b32_e32 v93, v136, v159, vcc
	v_pk_mul_f32 v[94:95], v[120:121], v[94:95]
	v_pk_fma_f32 v[90:91], v[114:115], v[90:91], v[96:97]
	v_pk_fma_f32 v[92:93], v[116:117], v[92:93], v[94:95]
	v_pk_fma_f32 v[86:87], v[86:87], v[106:107], v[90:91]
	v_mov_b32_dpp v149, v82 row_ror:1 row_mask:0xf bank_mask:0xf
	v_mov_b32_dpp v150, v82 row_ror:2 row_mask:0xf bank_mask:0xf
	v_mov_b32_dpp v151, v83 row_ror:1 row_mask:0xf bank_mask:0xf
	v_mov_b32_dpp v152, v83 row_ror:2 row_mask:0xf bank_mask:0xf
	v_mov_b32_dpp v153, v84 row_ror:1 row_mask:0xf bank_mask:0xf
	v_mov_b32_dpp v154, v84 row_ror:2 row_mask:0xf bank_mask:0xf
	v_mov_b32_dpp v155, v85 row_ror:1 row_mask:0xf bank_mask:0xf
	v_mov_b32_dpp v156, v85 row_ror:2 row_mask:0xf bank_mask:0xf
	v_pk_fma_f32 v[88:89], v[88:89], v[108:109], v[92:93]
	v_cndmask_b32_e64 v94, v143, v154, s[42:43]
	v_cndmask_b32_e64 v95, v145, v156, s[42:43]
	v_pk_add_f32 v[86:87], v[102:103], v[86:87]
	v_cndmask_b32_e32 v92, v153, v142, vcc
	v_cndmask_b32_e32 v93, v155, v144, vcc
; __device__ __forceinline__ unsigned cvt_pk_bf16(float lo, float hi) { unsigned r; asm volatile("v_cvt_pk_bf16_f32 %0, %1, %2" : "=v"(r) : "v"(lo), "v"(hi)); return r; }
; DI float dpp_ror1(float x) { float r; asm volatile("s_nop 1\n\tv_mov_b32_dpp %0, %1 row_ror:1 row_mask:0xf bank_mask:0xf" : "=v"(r) : "v"(x)); return r; }
; DI float dpp_ror2(float x) { float r; asm volatile("s_nop 1\n\tv_mov_b32_dpp %0, %1 row_ror:2 row_mask:0xf bank_mask:0xf" : "=v"(r) : "v"(x)); return r; }
;     __device__ __forceinline__ void operator()(const f32x4 (&acc)[2][2][4][2], const Unit& u, int wr, int wc, int fr_in, int fq_in) const {
;     ...
;                 for (int m = 0; m < 4; ++m) {
;                     f32x4 uu[2];
; #pragma unroll
;                     for (int bj = 0; bj < 2; ++bj) {
;                         const f32x4 cur = acc[ai][bj][m][n];
;                         f32x4 r1, r2;
; #pragma unroll
;                         for (int j = 0; j < 4; ++j) { r1[j] = dpp_ror1(cur[j]); r2[j] = dpp_ror2(cur[j]); }
;                         const f32x4 p1 = (fr >= 1) ? r1 : r1p[bj], p2 = (fr >= 2) ? r2 : r2p[bj];
;                         uu[bj] = w0[bj] * p2 + w1[bj] * p1 + w2[bj] * cur + bb[bj];
;                         r1p[bj] = r1; r2p[bj] = r2;
;                     }
;                     const int row = row0 + ai * HALF + m * 16;
;                     float a[4];
; #pragma unroll
;                     for (int j = 0; j < 4; ++j) { const float g = uu[0][j]; a[j] = g * __builtin_amdgcn_rcpf(1.f + __expf(-g)) * uu[1][j]; }
;                     u32x2 w; w.x = cvt_pk_bf16(a[0], a[1]); w.y = cvt_pk_bf16(a[2], a[3]);
;                     *(u32x2*)(ACT + (size_t)row * FFN + u.pn * HALF + wc * 32 + 8 * fq + 4 * n) = w;
	v_pk_mul_f32 v[94:95], v[128:129], v[94:95]
	v_cndmask_b32_e64 v96, v139, v150, s[42:43]
	v_pk_fma_f32 v[92:93], v[124:125], v[92:93], v[94:95]
	v_mul_f32_e32 v94, 0xbfb8aa3b, v86
	v_exp_f32_e32 v94, v94
	v_cndmask_b32_e64 v97, v141, v152, s[42:43]
	v_cndmask_b32_e32 v90, v149, v138, vcc
	v_cndmask_b32_e32 v91, v151, v140, vcc
	v_pk_mul_f32 v[96:97], v[126:127], v[96:97]
	v_pk_add_f32 v[88:89], v[104:105], v[88:89]
	v_pk_fma_f32 v[90:91], v[122:123], v[90:91], v[96:97]
	v_pk_fma_f32 v[84:85], v[84:85], v[112:113], v[92:93]
	v_pk_fma_f32 v[82:83], v[82:83], v[110:111], v[90:91]
	v_add_f32_e32 v90, 1.0, v94
	v_rcp_f32_e32 v90, v90
	v_mul_f32_e32 v91, 0xbfb8aa3b, v87
	v_exp_f32_e32 v91, v91
	v_pk_add_f32 v[82:83], v[98:99], v[82:83]
	v_mul_f32_e32 v86, v86, v90
	v_mul_f32_e32 v82, v86, v82
	v_add_f32_e32 v86, 1.0, v91
	v_mul_f32_e32 v90, 0xbfb8aa3b, v88
	v_rcp_f32_e32 v86, v86
	v_exp_f32_e32 v90, v90
	v_mul_f32_e32 v91, 0xbfb8aa3b, v89
	v_exp_f32_e32 v91, v91
	v_mul_f32_e32 v86, v87, v86
	v_add_f32_e32 v87, 1.0, v90
	v_rcp_f32_e32 v87, v87
	v_add_f32_e32 v90, 1.0, v91
	v_rcp_f32_e32 v90, v90
	v_pk_add_f32 v[84:85], v[100:101], v[84:85]
	v_mul_f32_e32 v83, v86, v83
	v_mul_f32_e32 v86, v88, v87
	v_mul_f32_e32 v84, v86, v84
	v_mul_f32_e32 v86, v89, v90
	v_mul_f32_e32 v85, v86, v85
	v_cvt_pk_bf16_f32 v82, v82, v83
	v_cvt_pk_bf16_f32 v83, v84, v85
	global_store_dwordx2 v[166:167], v[82:83], off offset:8
	v_mov_b32_dpp v90, v78 row_ror:1 row_mask:0xf bank_mask:0xf
	v_mov_b32_dpp v91, v78 row_ror:2 row_mask:0xf bank_mask:0xf
	v_mov_b32_dpp v92, v79 row_ror:1 row_mask:0xf bank_mask:0xf
	v_mov_b32_dpp v93, v79 row_ror:2 row_mask:0xf bank_mask:0xf
	v_mov_b32_dpp v94, v80 row_ror:1 row_mask:0xf bank_mask:0xf
	v_mov_b32_dpp v95, v80 row_ror:2 row_mask:0xf bank_mask:0xf
	v_mov_b32_dpp v96, v81 row_ror:1 row_mask:0xf bank_mask:0xf
	s_nop 0
	v_cndmask_b32_e64 v88, v131, v91, s[42:43]
	v_cndmask_b32_e64 v89, v133, v93, s[42:43]
	v_mov_b32_dpp v97, v81 row_ror:2 row_mask:0xf bank_mask:0xf
	v_cndmask_b32_e32 v82, v90, v130, vcc
	v_cndmask_b32_e32 v83, v92, v132, vcc
	v_cndmask_b32_e64 v86, v135, v95, s[42:43]
	v_cndmask_b32_e64 v87, v137, v97, s[42:43]
	v_pk_mul_f32 v[88:89], v[118:119], v[88:89]
	v_cndmask_b32_e32 v84, v94, v134, vcc
	v_cndmask_b32_e32 v85, v96, v136, vcc
	v_pk_mul_f32 v[86:87], v[120:121], v[86:87]
	v_pk_fma_f32 v[82:83], v[114:115], v[82:83], v[88:89]
	v_pk_fma_f32 v[84:85], v[116:117], v[84:85], v[86:87]
	v_pk_fma_f32 v[78:79], v[78:79], v[106:107], v[82:83]
	v_mov_b32_dpp v130, v74 row_ror:1 row_mask:0xf bank_mask:0xf
	v_mov_b32_dpp v131, v74 row_ror:2 row_mask:0xf bank_mask:0xf
	v_mov_b32_dpp v132, v75 row_ror:1 row_mask:0xf bank_mask:0xf
	v_mov_b32_dpp v133, v75 row_ror:2 row_mask:0xf bank_mask:0xf
	v_mov_b32_dpp v134, v76 row_ror:1 row_mask:0xf bank_mask:0xf
	v_mov_b32_dpp v135, v76 row_ror:2 row_mask:0xf bank_mask:0xf
	v_mov_b32_dpp v136, v77 row_ror:1 row_mask:0xf bank_mask:0xf
	v_mov_b32_dpp v137, v77 row_ror:2 row_mask:0xf bank_mask:0xf
	v_pk_fma_f32 v[80:81], v[80:81], v[108:109], v[84:85]
	v_cndmask_b32_e64 v86, v154, v135, s[42:43]
	v_cndmask_b32_e64 v87, v156, v137, s[42:43]
	v_pk_add_f32 v[78:79], v[102:103], v[78:79]
	v_cndmask_b32_e32 v84, v134, v153, vcc
	v_cndmask_b32_e32 v85, v136, v155, vcc
	v_pk_mul_f32 v[86:87], v[128:129], v[86:87]
	v_cndmask_b32_e64 v88, v150, v131, s[42:43]
	v_pk_fma_f32 v[84:85], v[124:125], v[84:85], v[86:87]
	v_mul_f32_e32 v86, 0xbfb8aa3b, v78
	v_exp_f32_e32 v86, v86
	v_cndmask_b32_e64 v89, v152, v133, s[42:43]
	v_cndmask_b32_e32 v82, v130, v149, vcc
	v_cndmask_b32_e32 v83, v132, v151, vcc
	v_pk_mul_f32 v[88:89], v[126:127], v[88:89]
	v_pk_add_f32 v[80:81], v[104:105], v[80:81]
	v_pk_fma_f32 v[82:83], v[122:123], v[82:83], v[88:89]
	v_pk_fma_f32 v[76:77], v[76:77], v[112:113], v[84:85]
	v_pk_fma_f32 v[74:75], v[74:75], v[110:111], v[82:83]
	v_add_f32_e32 v82, 1.0, v86
	v_rcp_f32_e32 v82, v82
	v_mul_f32_e32 v83, 0xbfb8aa3b, v79
	v_exp_f32_e32 v83, v83
	v_pk_add_f32 v[74:75], v[98:99], v[74:75]
	v_mul_f32_e32 v78, v78, v82
	v_mul_f32_e32 v74, v78, v74
	v_add_f32_e32 v78, 1.0, v83
	v_mul_f32_e32 v82, 0xbfb8aa3b, v80
	v_rcp_f32_e32 v78, v78
	v_exp_f32_e32 v82, v82
	v_mul_f32_e32 v83, 0xbfb8aa3b, v81
	v_exp_f32_e32 v83, v83
; DI float dpp_ror1(float x) { float r; asm volatile("s_nop 1\n\tv_mov_b32_dpp %0, %1 row_ror:1 row_mask:0xf bank_mask:0xf" : "=v"(r) : "v"(x)); return r; }
;     __device__ __forceinline__ void operator()(const f32x4 (&acc)[2][2][4][2], const Unit& u, int wr, int wc, int fr_in, int fq_in) const {
;     ...
; #pragma unroll
;                 for (int bj = 0; bj < 2; ++bj) {
;                     const int tcol = bj * HALF + wc * 32 + 8 * fq + 4 * n;
;                     w0[bj] = *(const f32x4*)(cwl + eo + tcol); w1[bj] = *(const f32x4*)(cwl + eo + 256 + tcol); w2[bj] = *(const f32x4*)(cwl + eo + 512 + tcol); bb[bj] = *(const f32x4*)(cwl + eo + 768 + tcol);
;                     f32x4 E0 = (f32x4){0.f, 0.f, 0.f, 0.f}, E1 = E0;
;                     if (fr < 2) {
;                         if (wr == 1 || ai == 1) {
;                             const int sai = (wr == 1) ? ai : 0, swr = (wr == 1) ? 0 : 1;
;                             const int e = (((((sai * 2 + swr) * 4 + wc) * 2 + bj) * 2 + n) * 4 + fq) * 2;
;                             E0 = ex[e]; E1 = ex[e + 1];
;                         }
;                     }
;                     r1p[bj] = E1; r2p[bj] = (fr == 0) ? E0 : E1;
;                 }
; #pragma unroll
;                 for (int m = 0; m < 4; ++m) {
;                     f32x4 uu[2];
; #pragma unroll
;                     for (int bj = 0; bj < 2; ++bj) {
;                         const f32x4 cur = acc[ai][bj][m][n];
;                         f32x4 r1, r2;
; #pragma unroll
;                         for (int j = 0; j < 4; ++j) { r1[j] = dpp_ror1(cur[j]); r2[j] = dpp_ror2(cur[j]); }
;                         const f32x4 p1 = (fr >= 1) ? r1 : r1p[bj], p2 = (fr >= 2) ? r2 : r2p[bj];
;                         uu[bj] = w0[bj] * p2 + w1[bj] * p1 + w2[bj] * cur + bb[bj];
;                         r1p[bj] = r1; r2p[bj] = r2;
;                     }
;                     const int row = row0 + ai * HALF + m * 16;
;                     float a[4];
; #pragma unroll
;                     for (int j = 0; j < 4; ++j) { const float g = uu[0][j]; a[j] = g * __builtin_amdgcn_rcpf(1.f + __expf(-g)) * uu[1][j]; }
;                     u32x2 w; w.x = cvt_pk_bf16(a[0], a[1]); w.y = cvt_pk_bf16(a[2], a[3]);
;                     *(u32x2*)(ACT + (size_t)row * FFN + u.pn * HALF + wc * 32 + 8 * fq + 4 * n) = w;
	v_mul_f32_e32 v78, v79, v78
	v_add_f32_e32 v79, 1.0, v82
	v_rcp_f32_e32 v79, v79
	v_add_f32_e32 v82, 1.0, v83
	v_rcp_f32_e32 v82, v82
	v_pk_add_f32 v[76:77], v[100:101], v[76:77]
	v_mul_f32_e32 v75, v78, v75
	v_mul_f32_e32 v78, v80, v79
	v_mul_f32_e32 v76, v78, v76
	v_mul_f32_e32 v78, v81, v82
	v_mul_f32_e32 v77, v78, v77
	v_cvt_pk_bf16_f32 v74, v74, v75
	v_cvt_pk_bf16_f32 v75, v76, v77
	global_store_dwordx2 v[168:169], v[74:75], off offset:8
	v_mov_b32_dpp v74, v70 row_ror:1 row_mask:0xf bank_mask:0xf
	v_mov_b32_dpp v80, v70 row_ror:2 row_mask:0xf bank_mask:0xf
	v_mov_b32_dpp v75, v71 row_ror:1 row_mask:0xf bank_mask:0xf
	v_mov_b32_dpp v81, v71 row_ror:2 row_mask:0xf bank_mask:0xf
	v_mov_b32_dpp v76, v72 row_ror:1 row_mask:0xf bank_mask:0xf
	v_mov_b32_dpp v78, v72 row_ror:2 row_mask:0xf bank_mask:0xf
	v_mov_b32_dpp v77, v73 row_ror:1 row_mask:0xf bank_mask:0xf
	v_mov_b32_dpp v79, v73 row_ror:2 row_mask:0xf bank_mask:0xf
	s_nop 0
	v_cndmask_b32_e64 v80, v91, v80, s[42:43]
	v_cndmask_b32_e64 v78, v95, v78, s[42:43]
	v_cndmask_b32_e64 v79, v97, v79, s[42:43]
	v_cndmask_b32_e64 v81, v93, v81, s[42:43]
	v_cndmask_b32_e32 v74, v74, v90, vcc
	v_cndmask_b32_e32 v75, v75, v92, vcc
	v_cndmask_b32_e32 v76, v76, v94, vcc
	v_cndmask_b32_e32 v77, v77, v96, vcc
	v_pk_mul_f32 v[80:81], v[118:119], v[80:81]
	v_pk_mul_f32 v[78:79], v[120:121], v[78:79]
	v_pk_fma_f32 v[74:75], v[114:115], v[74:75], v[80:81]
	v_pk_fma_f32 v[76:77], v[116:117], v[76:77], v[78:79]
	v_pk_fma_f32 v[70:71], v[70:71], v[106:107], v[74:75]
	v_pk_fma_f32 v[72:73], v[72:73], v[108:109], v[76:77]
	v_mov_b32_dpp v74, v66 row_ror:1 row_mask:0xf bank_mask:0xf
	v_mov_b32_dpp v80, v66 row_ror:2 row_mask:0xf bank_mask:0xf
	v_mov_b32_dpp v75, v67 row_ror:1 row_mask:0xf bank_mask:0xf
	v_mov_b32_dpp v81, v67 row_ror:2 row_mask:0xf bank_mask:0xf
	v_mov_b32_dpp v76, v68 row_ror:1 row_mask:0xf bank_mask:0xf
	v_mov_b32_dpp v78, v68 row_ror:2 row_mask:0xf bank_mask:0xf
	v_mov_b32_dpp v77, v69 row_ror:1 row_mask:0xf bank_mask:0xf
	v_mov_b32_dpp v79, v69 row_ror:2 row_mask:0xf bank_mask:0xf
	v_pk_add_f32 v[70:71], v[102:103], v[70:71]
	v_cndmask_b32_e64 v78, v135, v78, s[42:43]
	v_cndmask_b32_e64 v79, v137, v79, s[42:43]
	v_cndmask_b32_e32 v76, v76, v134, vcc
	v_cndmask_b32_e32 v77, v77, v136, vcc
	v_pk_mul_f32 v[78:79], v[128:129], v[78:79]
	v_cndmask_b32_e64 v80, v131, v80, s[42:43]
	v_pk_fma_f32 v[76:77], v[124:125], v[76:77], v[78:79]
	v_mul_f32_e32 v78, 0xbfb8aa3b, v70
	v_exp_f32_e32 v78, v78
	v_cndmask_b32_e64 v81, v133, v81, s[42:43]
	v_cndmask_b32_e32 v74, v74, v130, vcc
	v_cndmask_b32_e32 v75, v75, v132, vcc
	v_pk_mul_f32 v[80:81], v[126:127], v[80:81]
	v_pk_add_f32 v[72:73], v[104:105], v[72:73]
	v_pk_fma_f32 v[74:75], v[122:123], v[74:75], v[80:81]
	v_pk_fma_f32 v[68:69], v[68:69], v[112:113], v[76:77]
	v_pk_fma_f32 v[66:67], v[66:67], v[110:111], v[74:75]
	v_add_f32_e32 v74, 1.0, v78
	v_rcp_f32_e32 v74, v74
	v_mul_f32_e32 v75, 0xbfb8aa3b, v71
	v_exp_f32_e32 v75, v75
	v_pk_add_f32 v[66:67], v[98:99], v[66:67]
	v_mul_f32_e32 v70, v70, v74
	v_mul_f32_e32 v66, v70, v66
	v_add_f32_e32 v70, 1.0, v75
	v_mul_f32_e32 v74, 0xbfb8aa3b, v72
	v_rcp_f32_e32 v70, v70
	v_exp_f32_e32 v74, v74
	v_mul_f32_e32 v75, 0xbfb8aa3b, v73
	v_exp_f32_e32 v75, v75
	v_mul_f32_e32 v70, v71, v70
	v_add_f32_e32 v71, 1.0, v74
	v_rcp_f32_e32 v71, v71
	v_add_f32_e32 v74, 1.0, v75
	v_rcp_f32_e32 v74, v74
	v_pk_add_f32 v[68:69], v[100:101], v[68:69]
	v_mul_f32_e32 v67, v70, v67
	v_mul_f32_e32 v70, v72, v71
	v_mul_f32_e32 v68, v70, v68
	v_mul_f32_e32 v70, v73, v74
	v_mul_f32_e32 v69, v70, v69
	v_cvt_pk_bf16_f32 v66, v66, v67
	v_cvt_pk_bf16_f32 v67, v68, v69
	global_store_dwordx2 v[146:147], v[66:67], off offset:8
	ds_read_b128 v[86:89], v214
	ds_read_b128 v[82:85], v214 offset:1024
	ds_read_b128 v[74:77], v214 offset:2048
	ds_read_b128 v[70:73], v214 offset:3072
	v_mov_b32_e32 v106, 0
	v_mov_b32_e32 v110, 0
	v_mov_b32_e32 v111, 0
	v_mov_b32_e32 v112, 0
	v_mov_b32_e32 v113, 0
	v_mov_b32_e32 v102, 0
	v_mov_b32_e32 v103, 0
	v_mov_b32_e32 v104, 0
	v_mov_b32_e32 v105, 0
	s_and_saveexec_b64 s[48:49], s[44:45]
	s_cbranch_execz .LBB0_726
	s_lshl_b32 s2, s97, 4
	v_add3_u32 v66, v213, v215, s2
	ds_read_b128 v[110:113], v66
	ds_read_b128 v[102:105], v66 offset:16

; __device__ __forceinline__ unsigned cvt_pk_bf16(float lo, float hi) { unsigned r; asm volatile("v_cvt_pk_bf16_f32 %0, %1, %2" : "=v"(r) : "v"(lo), "v"(hi)); return r; }
; DI float dpp_ror1(float x) { float r; asm volatile("s_nop 1\n\tv_mov_b32_dpp %0, %1 row_ror:1 row_mask:0xf bank_mask:0xf" : "=v"(r) : "v"(x)); return r; }
; DI float dpp_ror2(float x) { float r; asm volatile("s_nop 1\n\tv_mov_b32_dpp %0, %1 row_ror:2 row_mask:0xf bank_mask:0xf" : "=v"(r) : "v"(x)); return r; }
;     __device__ __forceinline__ void operator()(const f32x4 (&acc)[2][2][4][2], const Unit& u, int wr, int wc, int fr_in, int fq_in) const {
;     ...
;                 for (int m = 0; m < 4; ++m) {
;                     f32x4 uu[2];
; #pragma unroll
;                     for (int bj = 0; bj < 2; ++bj) {
;                         const f32x4 cur = acc[ai][bj][m][n];
;                         f32x4 r1, r2;
; #pragma unroll
;                         for (int j = 0; j < 4; ++j) { r1[j] = dpp_ror1(cur[j]); r2[j] = dpp_ror2(cur[j]); }
;                         const f32x4 p1 = (fr >= 1) ? r1 : r1p[bj], p2 = (fr >= 2) ? r2 : r2p[bj];
;                         uu[bj] = w0[bj] * p2 + w1[bj] * p1 + w2[bj] * cur + bb[bj];
;                         r1p[bj] = r1; r2p[bj] = r2;
;                     }
;                     const int row = row0 + ai * HALF + m * 16;
;                     float a[4];
; #pragma unroll
;                     for (int j = 0; j < 4; ++j) { const float g = uu[0][j]; a[j] = g * __builtin_amdgcn_rcpf(1.f + __expf(-g)) * uu[1][j]; }
;                     u32x2 w; w.x = cvt_pk_bf16(a[0], a[1]); w.y = cvt_pk_bf16(a[2], a[3]);
;                     *(u32x2*)(ACT + (size_t)row * FFN + u.pn * HALF + wc * 32 + 8 * fq + 4 * n) = w;
.LBB0_728:
	s_or_b64 exec, exec, s[48:49]
	s_waitcnt lgkmcnt(0)
	v_cndmask_b32_e32 v111, v103, v111, vcc
	v_cndmask_b32_e32 v110, v102, v110, vcc
	v_cndmask_b32_e32 v113, v105, v113, vcc
	v_cndmask_b32_e32 v112, v104, v112, vcc
	v_cndmask_b32_e32 v117, v101, v109, vcc
	v_cndmask_b32_e32 v118, v100, v108, vcc
	v_mov_b32_dpp v119, v62 row_ror:1 row_mask:0xf bank_mask:0xf
	v_mov_b32_dpp v120, v62 row_ror:2 row_mask:0xf bank_mask:0xf
	v_mov_b32_dpp v121, v63 row_ror:1 row_mask:0xf bank_mask:0xf
	v_mov_b32_dpp v122, v63 row_ror:2 row_mask:0xf bank_mask:0xf
	v_cndmask_b32_e32 v115, v99, v107, vcc
	v_cndmask_b32_e64 v108, v110, v120, s[42:43]
	v_cndmask_b32_e64 v109, v111, v122, s[42:43]
	v_cndmask_b32_e32 v116, v98, v106, vcc
	v_mov_b32_dpp v123, v64 row_ror:1 row_mask:0xf bank_mask:0xf
	v_mov_b32_dpp v124, v64 row_ror:2 row_mask:0xf bank_mask:0xf
	v_mov_b32_dpp v125, v65 row_ror:1 row_mask:0xf bank_mask:0xf
	v_mov_b32_dpp v126, v65 row_ror:2 row_mask:0xf bank_mask:0xf
	v_cndmask_b32_e32 v102, v119, v102, vcc
	v_cndmask_b32_e32 v103, v121, v103, vcc
	v_cndmask_b32_e64 v106, v112, v124, s[42:43]
	v_cndmask_b32_e64 v107, v113, v126, s[42:43]
	v_pk_mul_f32 v[108:109], v[86:87], v[108:109]
	v_cndmask_b32_e32 v104, v123, v104, vcc
	v_cndmask_b32_e32 v105, v125, v105, vcc
	v_pk_mul_f32 v[106:107], v[88:89], v[106:107]
	v_pk_fma_f32 v[102:103], v[82:83], v[102:103], v[108:109]
	v_pk_fma_f32 v[104:105], v[84:85], v[104:105], v[106:107]
	v_pk_fma_f32 v[62:63], v[62:63], v[74:75], v[102:103]
	v_mov_b32_dpp v106, v58 row_ror:1 row_mask:0xf bank_mask:0xf
	v_mov_b32_dpp v107, v58 row_ror:2 row_mask:0xf bank_mask:0xf
	v_mov_b32_dpp v108, v59 row_ror:1 row_mask:0xf bank_mask:0xf
	v_mov_b32_dpp v109, v59 row_ror:2 row_mask:0xf bank_mask:0xf
	v_mov_b32_dpp v110, v60 row_ror:1 row_mask:0xf bank_mask:0xf
	v_mov_b32_dpp v111, v60 row_ror:2 row_mask:0xf bank_mask:0xf
	v_mov_b32_dpp v112, v61 row_ror:1 row_mask:0xf bank_mask:0xf
	v_mov_b32_dpp v113, v61 row_ror:2 row_mask:0xf bank_mask:0xf
	s_nop 0
	v_pk_add_f32 v[62:63], v[70:71], v[62:63]
	v_cndmask_b32_e64 v102, v118, v111, s[42:43]
	v_cndmask_b32_e64 v103, v117, v113, s[42:43]
	v_cndmask_b32_e32 v100, v110, v100, vcc
	v_cndmask_b32_e32 v101, v112, v101, vcc
	v_pk_mul_f32 v[102:103], v[96:97], v[102:103]
	v_pk_fma_f32 v[64:65], v[64:65], v[76:77], v[104:105]
	v_pk_fma_f32 v[100:101], v[92:93], v[100:101], v[102:103]
	v_mul_f32_e32 v102, 0xbfb8aa3b, v62
	v_exp_f32_e32 v102, v102
	v_cndmask_b32_e64 v104, v116, v107, s[42:43]
	v_cndmask_b32_e64 v105, v115, v109, s[42:43]
	v_cndmask_b32_e32 v98, v106, v98, vcc
	v_cndmask_b32_e32 v99, v108, v99, vcc
	v_pk_mul_f32 v[104:105], v[94:95], v[104:105]
	v_pk_add_f32 v[64:65], v[72:73], v[64:65]
	v_pk_fma_f32 v[98:99], v[90:91], v[98:99], v[104:105]
	v_pk_fma_f32 v[60:61], v[60:61], v[80:81], v[100:101]
	v_pk_fma_f32 v[58:59], v[58:59], v[78:79], v[98:99]
	v_add_f32_e32 v98, 1.0, v102
	v_rcp_f32_e32 v98, v98
	v_mul_f32_e32 v99, 0xbfb8aa3b, v63
	v_exp_f32_e32 v99, v99
	v_pk_add_f32 v[58:59], v[66:67], v[58:59]
	v_mul_f32_e32 v62, v62, v98
	v_mul_f32_e32 v58, v62, v58
	v_add_f32_e32 v62, 1.0, v99
	v_mul_f32_e32 v98, 0xbfb8aa3b, v64
	v_rcp_f32_e32 v62, v62
	v_exp_f32_e32 v98, v98
	v_mul_f32_e32 v99, 0xbfb8aa3b, v65
	v_exp_f32_e32 v99, v99
	v_mul_f32_e32 v62, v63, v62
	v_add_f32_e32 v63, 1.0, v98
	v_rcp_f32_e32 v63, v63
	v_add_f32_e32 v98, 1.0, v99
	v_rcp_f32_e32 v98, v98
	v_pk_add_f32 v[60:61], v[68:69], v[60:61]
	v_mul_f32_e32 v59, v62, v59
	v_mul_f32_e32 v62, v64, v63
	v_readlane_b32 s8, v240, 27
	v_mul_f32_e32 v62, v62, v60
	v_mul_f32_e32 v60, v65, v98
	v_readlane_b32 s9, v240, 28
	v_add_u32_e32 v114, 0x80, v174
	v_mul_f32_e32 v61, v60, v61
	v_cvt_pk_bf16_f32 v60, v58, v59
	v_mov_b64_e32 v[58:59], s[8:9]
	v_cvt_pk_bf16_f32 v61, v62, v61
	v_mad_i64_i32 v[62:63], s[22:23], v114, s25, v[58:59]
	v_lshl_add_u64 v[62:63], v[62:63], 0, s[46:47]
	v_lshl_add_u64 v[62:63], v[62:63], 0, s[62:63]
	v_lshl_add_u64 v[98:99], v[62:63], 0, v[162:163]
	global_store_dwordx2 v[98:99], v[60:61], off
	v_mov_b32_dpp v102, v54 row_ror:1 row_mask:0xf bank_mask:0xf
	v_mov_b32_dpp v103, v54 row_ror:2 row_mask:0xf bank_mask:0xf
	v_mov_b32_dpp v104, v55 row_ror:1 row_mask:0xf bank_mask:0xf
	v_mov_b32_dpp v105, v55 row_ror:2 row_mask:0xf bank_mask:0xf
	v_mov_b32_dpp v114, v56 row_ror:1 row_mask:0xf bank_mask:0xf
	v_mov_b32_dpp v115, v56 row_ror:2 row_mask:0xf bank_mask:0xf
	v_mov_b32_dpp v116, v57 row_ror:1 row_mask:0xf bank_mask:0xf
	s_nop 0
	v_cndmask_b32_e64 v100, v120, v103, s[42:43]
	v_cndmask_b32_e64 v101, v122, v105, s[42:43]
	v_mov_b32_dpp v117, v57 row_ror:2 row_mask:0xf bank_mask:0xf
	v_cndmask_b32_e32 v60, v102, v119, vcc
	v_cndmask_b32_e32 v61, v104, v121, vcc
	v_cndmask_b32_e64 v64, v124, v115, s[42:43]
	v_cndmask_b32_e64 v65, v126, v117, s[42:43]
	v_pk_mul_f32 v[100:101], v[86:87], v[100:101]
	v_cndmask_b32_e32 v62, v114, v123, vcc
	v_cndmask_b32_e32 v63, v116, v125, vcc
	v_pk_mul_f32 v[64:65], v[88:89], v[64:65]
	v_pk_fma_f32 v[60:61], v[82:83], v[60:61], v[100:101]
	v_pk_fma_f32 v[62:63], v[84:85], v[62:63], v[64:65]
	v_pk_fma_f32 v[54:55], v[54:55], v[74:75], v[60:61]
	v_mov_b32_dpp v118, v50 row_ror:1 row_mask:0xf bank_mask:0xf
	v_mov_b32_dpp v119, v50 row_ror:2 row_mask:0xf bank_mask:0xf
	v_mov_b32_dpp v120, v51 row_ror:1 row_mask:0xf bank_mask:0xf
	v_mov_b32_dpp v121, v51 row_ror:2 row_mask:0xf bank_mask:0xf
	v_mov_b32_dpp v122, v52 row_ror:1 row_mask:0xf bank_mask:0xf
	v_mov_b32_dpp v123, v52 row_ror:2 row_mask:0xf bank_mask:0xf
	v_mov_b32_dpp v124, v53 row_ror:1 row_mask:0xf bank_mask:0xf
	v_mov_b32_dpp v125, v53 row_ror:2 row_mask:0xf bank_mask:0xf
	v_pk_fma_f32 v[56:57], v[56:57], v[76:77], v[62:63]
; __device__ __forceinline__ unsigned cvt_pk_bf16(float lo, float hi) { unsigned r; asm volatile("v_cvt_pk_bf16_f32 %0, %1, %2" : "=v"(r) : "v"(lo), "v"(hi)); return r; }
; DI float dpp_ror1(float x) { float r; asm volatile("s_nop 1\n\tv_mov_b32_dpp %0, %1 row_ror:1 row_mask:0xf bank_mask:0xf" : "=v"(r) : "v"(x)); return r; }
; DI float dpp_ror2(float x) { float r; asm volatile("s_nop 1\n\tv_mov_b32_dpp %0, %1 row_ror:2 row_mask:0xf bank_mask:0xf" : "=v"(r) : "v"(x)); return r; }
;     __device__ __forceinline__ void operator()(const f32x4 (&acc)[2][2][4][2], const Unit& u, int wr, int wc, int fr_in, int fq_in) const {
;     ...
;                 for (int m = 0; m < 4; ++m) {
;                     f32x4 uu[2];
; #pragma unroll
;                     for (int bj = 0; bj < 2; ++bj) {
;                         const f32x4 cur = acc[ai][bj][m][n];
;                         f32x4 r1, r2;
; #pragma unroll
;                         for (int j = 0; j < 4; ++j) { r1[j] = dpp_ror1(cur[j]); r2[j] = dpp_ror2(cur[j]); }
;                         const f32x4 p1 = (fr >= 1) ? r1 : r1p[bj], p2 = (fr >= 2) ? r2 : r2p[bj];
;                         uu[bj] = w0[bj] * p2 + w1[bj] * p1 + w2[bj] * cur + bb[bj];
;                         r1p[bj] = r1; r2p[bj] = r2;
;                     }
;                     const int row = row0 + ai * HALF + m * 16;
;                     float a[4];
; #pragma unroll
;                     for (int j = 0; j < 4; ++j) { const float g = uu[0][j]; a[j] = g * __builtin_amdgcn_rcpf(1.f + __expf(-g)) * uu[1][j]; }
;                     u32x2 w; w.x = cvt_pk_bf16(a[0], a[1]); w.y = cvt_pk_bf16(a[2], a[3]);
;                     *(u32x2*)(ACT + (size_t)row * FFN + u.pn * HALF + wc * 32 + 8 * fq + 4 * n) = w;
	v_cndmask_b32_e64 v64, v111, v123, s[42:43]
	v_cndmask_b32_e64 v65, v113, v125, s[42:43]
	v_pk_add_f32 v[54:55], v[70:71], v[54:55]
	v_cndmask_b32_e32 v62, v122, v110, vcc
	v_cndmask_b32_e32 v63, v124, v112, vcc
	v_pk_mul_f32 v[64:65], v[96:97], v[64:65]
	v_cndmask_b32_e64 v100, v107, v119, s[42:43]
	v_pk_fma_f32 v[62:63], v[92:93], v[62:63], v[64:65]
	v_mul_f32_e32 v64, 0xbfb8aa3b, v54
	v_exp_f32_e32 v64, v64
	v_cndmask_b32_e64 v101, v109, v121, s[42:43]
	v_cndmask_b32_e32 v60, v118, v106, vcc
	v_cndmask_b32_e32 v61, v120, v108, vcc
	v_pk_mul_f32 v[100:101], v[94:95], v[100:101]
	v_pk_add_f32 v[56:57], v[72:73], v[56:57]
	v_pk_fma_f32 v[60:61], v[90:91], v[60:61], v[100:101]
	v_pk_fma_f32 v[52:53], v[52:53], v[80:81], v[62:63]
	v_pk_fma_f32 v[50:51], v[50:51], v[78:79], v[60:61]
	v_add_f32_e32 v60, 1.0, v64
	v_rcp_f32_e32 v60, v60
	v_mul_f32_e32 v61, 0xbfb8aa3b, v55
	v_exp_f32_e32 v61, v61
	v_pk_add_f32 v[50:51], v[66:67], v[50:51]
	v_mul_f32_e32 v54, v54, v60
	v_mul_f32_e32 v50, v54, v50
	v_add_f32_e32 v54, 1.0, v61
	v_mul_f32_e32 v60, 0xbfb8aa3b, v56
	v_rcp_f32_e32 v54, v54
	v_exp_f32_e32 v60, v60
	v_mul_f32_e32 v61, 0xbfb8aa3b, v57
	v_exp_f32_e32 v61, v61
	v_mul_f32_e32 v54, v55, v54
	v_add_f32_e32 v55, 1.0, v60
	v_rcp_f32_e32 v55, v55
	v_add_f32_e32 v60, 1.0, v61
	v_rcp_f32_e32 v60, v60
	v_pk_add_f32 v[52:53], v[68:69], v[52:53]
	v_mul_f32_e32 v51, v54, v51
	v_mul_f32_e32 v54, v56, v55
	v_mul_f32_e32 v52, v54, v52
	v_mul_f32_e32 v54, v57, v60
	v_mul_f32_e32 v53, v54, v53
	v_add_u32_e32 v54, 0x90, v174
	v_cvt_pk_bf16_f32 v50, v50, v51
	v_cvt_pk_bf16_f32 v51, v52, v53
	v_mad_i64_i32 v[52:53], s[22:23], v54, s25, v[58:59]
	v_lshl_add_u64 v[52:53], v[52:53], 0, s[46:47]
	v_lshl_add_u64 v[52:53], v[52:53], 0, s[62:63]
	v_lshl_add_u64 v[100:101], v[52:53], 0, v[162:163]
	global_store_dwordx2 v[100:101], v[50:51], off
	v_mov_b32_dpp v60, v46 row_ror:1 row_mask:0xf bank_mask:0xf
	v_mov_b32_dpp v61, v46 row_ror:2 row_mask:0xf bank_mask:0xf
	v_mov_b32_dpp v62, v47 row_ror:1 row_mask:0xf bank_mask:0xf
	v_mov_b32_dpp v63, v47 row_ror:2 row_mask:0xf bank_mask:0xf
	v_mov_b32_dpp v64, v48 row_ror:1 row_mask:0xf bank_mask:0xf
	v_mov_b32_dpp v65, v48 row_ror:2 row_mask:0xf bank_mask:0xf
	v_mov_b32_dpp v106, v49 row_ror:1 row_mask:0xf bank_mask:0xf
	s_nop 0
	v_cndmask_b32_e64 v56, v103, v61, s[42:43]
	v_cndmask_b32_e64 v57, v105, v63, s[42:43]
	v_mov_b32_dpp v107, v49 row_ror:2 row_mask:0xf bank_mask:0xf
	v_cndmask_b32_e32 v50, v60, v102, vcc
	v_cndmask_b32_e32 v51, v62, v104, vcc
	v_cndmask_b32_e64 v54, v115, v65, s[42:43]
	v_cndmask_b32_e64 v55, v117, v107, s[42:43]
	v_pk_mul_f32 v[56:57], v[86:87], v[56:57]
	v_cndmask_b32_e32 v52, v64, v114, vcc
	v_cndmask_b32_e32 v53, v106, v116, vcc
	v_pk_mul_f32 v[54:55], v[88:89], v[54:55]
	v_pk_fma_f32 v[50:51], v[82:83], v[50:51], v[56:57]
	v_pk_fma_f32 v[52:53], v[84:85], v[52:53], v[54:55]
	v_pk_fma_f32 v[46:47], v[46:47], v[74:75], v[50:51]
	v_mov_b32_dpp v104, v42 row_ror:1 row_mask:0xf bank_mask:0xf
	v_mov_b32_dpp v105, v42 row_ror:2 row_mask:0xf bank_mask:0xf
	v_mov_b32_dpp v108, v43 row_ror:1 row_mask:0xf bank_mask:0xf
	v_mov_b32_dpp v109, v43 row_ror:2 row_mask:0xf bank_mask:0xf
	v_mov_b32_dpp v110, v44 row_ror:1 row_mask:0xf bank_mask:0xf
	v_mov_b32_dpp v111, v44 row_ror:2 row_mask:0xf bank_mask:0xf
	v_mov_b32_dpp v112, v45 row_ror:1 row_mask:0xf bank_mask:0xf
	v_mov_b32_dpp v113, v45 row_ror:2 row_mask:0xf bank_mask:0xf
	v_pk_fma_f32 v[48:49], v[48:49], v[76:77], v[52:53]
	v_cndmask_b32_e64 v54, v123, v111, s[42:43]
	v_cndmask_b32_e64 v55, v125, v113, s[42:43]
	v_pk_add_f32 v[46:47], v[70:71], v[46:47]
	v_cndmask_b32_e32 v52, v110, v122, vcc
	v_cndmask_b32_e32 v53, v112, v124, vcc
	v_pk_mul_f32 v[54:55], v[96:97], v[54:55]
	v_cndmask_b32_e64 v56, v119, v105, s[42:43]
	v_pk_fma_f32 v[52:53], v[92:93], v[52:53], v[54:55]
	v_mul_f32_e32 v54, 0xbfb8aa3b, v46
	v_exp_f32_e32 v54, v54
	v_cndmask_b32_e64 v57, v121, v109, s[42:43]
	v_cndmask_b32_e32 v50, v104, v118, vcc
	v_cndmask_b32_e32 v51, v108, v120, vcc
	v_pk_mul_f32 v[56:57], v[94:95], v[56:57]
	v_pk_add_f32 v[48:49], v[72:73], v[48:49]
	v_pk_fma_f32 v[50:51], v[90:91], v[50:51], v[56:57]
	v_pk_fma_f32 v[44:45], v[44:45], v[80:81], v[52:53]
	v_pk_fma_f32 v[42:43], v[42:43], v[78:79], v[50:51]
	v_add_f32_e32 v50, 1.0, v54
	v_rcp_f32_e32 v50, v50
	v_mul_f32_e32 v51, 0xbfb8aa3b, v47
	v_exp_f32_e32 v51, v51
	v_pk_add_f32 v[42:43], v[66:67], v[42:43]
	v_mul_f32_e32 v46, v46, v50
	v_mul_f32_e32 v42, v46, v42
	v_add_f32_e32 v46, 1.0, v51
	v_mul_f32_e32 v50, 0xbfb8aa3b, v48
	v_rcp_f32_e32 v46, v46
	v_exp_f32_e32 v50, v50
	v_mul_f32_e32 v51, 0xbfb8aa3b, v49
	v_exp_f32_e32 v51, v51
; __device__ __forceinline__ unsigned cvt_pk_bf16(float lo, float hi) { unsigned r; asm volatile("v_cvt_pk_bf16_f32 %0, %1, %2" : "=v"(r) : "v"(lo), "v"(hi)); return r; }
; DI float dpp_ror1(float x) { float r; asm volatile("s_nop 1\n\tv_mov_b32_dpp %0, %1 row_ror:1 row_mask:0xf bank_mask:0xf" : "=v"(r) : "v"(x)); return r; }
;     __device__ __forceinline__ void operator()(const f32x4 (&acc)[2][2][4][2], const Unit& u, int wr, int wc, int fr_in, int fq_in) const {
;     ...
;                 for (int bj = 0; bj < 2; ++bj) {
;                     const int tcol = bj * HALF + wc * 32 + 8 * fq + 4 * n;
;                     w0[bj] = *(const f32x4*)(cwl + eo + tcol); w1[bj] = *(const f32x4*)(cwl + eo + 256 + tcol); w2[bj] = *(const f32x4*)(cwl + eo + 512 + tcol); bb[bj] = *(const f32x4*)(cwl + eo + 768 + tcol);
;                     f32x4 E0 = (f32x4){0.f, 0.f, 0.f, 0.f}, E1 = E0;
;                     if (fr < 2) {
;                         if (wr == 1 || ai == 1) {
;                             const int sai = (wr == 1) ? ai : 0, swr = (wr == 1) ? 0 : 1;
;                             const int e = (((((sai * 2 + swr) * 4 + wc) * 2 + bj) * 2 + n) * 4 + fq) * 2;
;                             E0 = ex[e]; E1 = ex[e + 1];
;                         }
;     ...
;                 for (int m = 0; m < 4; ++m) {
;                     f32x4 uu[2];
; #pragma unroll
;                     for (int bj = 0; bj < 2; ++bj) {
;                         const f32x4 cur = acc[ai][bj][m][n];
;                         f32x4 r1, r2;
; #pragma unroll
;                         for (int j = 0; j < 4; ++j) { r1[j] = dpp_ror1(cur[j]); r2[j] = dpp_ror2(cur[j]); }
;                         const f32x4 p1 = (fr >= 1) ? r1 : r1p[bj], p2 = (fr >= 2) ? r2 : r2p[bj];
;                         uu[bj] = w0[bj] * p2 + w1[bj] * p1 + w2[bj] * cur + bb[bj];
;                         r1p[bj] = r1; r2p[bj] = r2;
;                     }
;                     const int row = row0 + ai * HALF + m * 16;
;                     float a[4];
; #pragma unroll
;                     for (int j = 0; j < 4; ++j) { const float g = uu[0][j]; a[j] = g * __builtin_amdgcn_rcpf(1.f + __expf(-g)) * uu[1][j]; }
;                     u32x2 w; w.x = cvt_pk_bf16(a[0], a[1]); w.y = cvt_pk_bf16(a[2], a[3]);
;                     *(u32x2*)(ACT + (size_t)row * FFN + u.pn * HALF + wc * 32 + 8 * fq + 4 * n) = w;
	v_mul_f32_e32 v46, v47, v46
	v_add_f32_e32 v47, 1.0, v50
	v_rcp_f32_e32 v47, v47
	v_add_f32_e32 v50, 1.0, v51
	v_rcp_f32_e32 v50, v50
	v_pk_add_f32 v[44:45], v[68:69], v[44:45]
	v_mul_f32_e32 v43, v46, v43
	v_mul_f32_e32 v46, v48, v47
	v_mul_f32_e32 v44, v46, v44
	v_mul_f32_e32 v46, v49, v50
	v_mul_f32_e32 v45, v46, v45
	v_add_u32_e32 v46, 0xa0, v174
	v_cvt_pk_bf16_f32 v42, v42, v43
	v_cvt_pk_bf16_f32 v43, v44, v45
	v_mad_i64_i32 v[44:45], s[22:23], v46, s25, v[58:59]
	v_lshl_add_u64 v[44:45], v[44:45], 0, s[46:47]
	v_lshl_add_u64 v[44:45], v[44:45], 0, s[62:63]
	v_lshl_add_u64 v[102:103], v[44:45], 0, v[162:163]
	global_store_dwordx2 v[102:103], v[42:43], off
	v_mov_b32_dpp v42, v38 row_ror:1 row_mask:0xf bank_mask:0xf
	v_mov_b32_dpp v48, v38 row_ror:2 row_mask:0xf bank_mask:0xf
	v_mov_b32_dpp v43, v39 row_ror:1 row_mask:0xf bank_mask:0xf
	v_mov_b32_dpp v49, v39 row_ror:2 row_mask:0xf bank_mask:0xf
	v_mov_b32_dpp v44, v40 row_ror:1 row_mask:0xf bank_mask:0xf
	v_mov_b32_dpp v46, v40 row_ror:2 row_mask:0xf bank_mask:0xf
	v_mov_b32_dpp v45, v41 row_ror:1 row_mask:0xf bank_mask:0xf
	v_mov_b32_dpp v47, v41 row_ror:2 row_mask:0xf bank_mask:0xf
	s_nop 0
	v_cndmask_b32_e64 v48, v61, v48, s[42:43]
	v_cndmask_b32_e64 v46, v65, v46, s[42:43]
	v_cndmask_b32_e64 v47, v107, v47, s[42:43]
	v_cndmask_b32_e64 v49, v63, v49, s[42:43]
	v_cndmask_b32_e32 v42, v42, v60, vcc
	v_cndmask_b32_e32 v43, v43, v62, vcc
	v_cndmask_b32_e32 v44, v44, v64, vcc
	v_cndmask_b32_e32 v45, v45, v106, vcc
	v_pk_mul_f32 v[48:49], v[86:87], v[48:49]
	v_pk_mul_f32 v[46:47], v[88:89], v[46:47]
	v_pk_fma_f32 v[42:43], v[82:83], v[42:43], v[48:49]
	v_pk_fma_f32 v[44:45], v[84:85], v[44:45], v[46:47]
	v_pk_fma_f32 v[38:39], v[38:39], v[74:75], v[42:43]
	v_pk_fma_f32 v[40:41], v[40:41], v[76:77], v[44:45]
	v_mov_b32_dpp v42, v34 row_ror:1 row_mask:0xf bank_mask:0xf
	v_mov_b32_dpp v48, v34 row_ror:2 row_mask:0xf bank_mask:0xf
	v_mov_b32_dpp v43, v35 row_ror:1 row_mask:0xf bank_mask:0xf
	v_mov_b32_dpp v49, v35 row_ror:2 row_mask:0xf bank_mask:0xf
	v_mov_b32_dpp v44, v36 row_ror:1 row_mask:0xf bank_mask:0xf
	v_mov_b32_dpp v46, v36 row_ror:2 row_mask:0xf bank_mask:0xf
	v_mov_b32_dpp v45, v37 row_ror:1 row_mask:0xf bank_mask:0xf
	v_mov_b32_dpp v47, v37 row_ror:2 row_mask:0xf bank_mask:0xf
	v_pk_add_f32 v[38:39], v[70:71], v[38:39]
	v_cndmask_b32_e64 v46, v111, v46, s[42:43]
	v_cndmask_b32_e64 v47, v113, v47, s[42:43]
	v_cndmask_b32_e32 v44, v44, v110, vcc
	v_cndmask_b32_e32 v45, v45, v112, vcc
	v_pk_mul_f32 v[46:47], v[96:97], v[46:47]
	v_cndmask_b32_e64 v48, v105, v48, s[42:43]
	v_pk_fma_f32 v[44:45], v[92:93], v[44:45], v[46:47]
	v_mul_f32_e32 v46, 0xbfb8aa3b, v38
	v_exp_f32_e32 v46, v46
	v_cndmask_b32_e64 v49, v109, v49, s[42:43]
	v_cndmask_b32_e32 v42, v42, v104, vcc
	v_cndmask_b32_e32 v43, v43, v108, vcc
	v_pk_mul_f32 v[48:49], v[94:95], v[48:49]
	v_pk_add_f32 v[40:41], v[72:73], v[40:41]
	v_pk_fma_f32 v[42:43], v[90:91], v[42:43], v[48:49]
	v_pk_fma_f32 v[36:37], v[36:37], v[80:81], v[44:45]
	v_pk_fma_f32 v[34:35], v[34:35], v[78:79], v[42:43]
	v_add_f32_e32 v42, 1.0, v46
	v_rcp_f32_e32 v42, v42
	v_mul_f32_e32 v43, 0xbfb8aa3b, v39
	v_exp_f32_e32 v43, v43
	v_pk_add_f32 v[34:35], v[66:67], v[34:35]
	v_mul_f32_e32 v38, v38, v42
	v_mul_f32_e32 v34, v38, v34
	v_add_f32_e32 v38, 1.0, v43
	v_mul_f32_e32 v42, 0xbfb8aa3b, v40
	v_rcp_f32_e32 v38, v38
	v_exp_f32_e32 v42, v42
	v_mul_f32_e32 v43, 0xbfb8aa3b, v41
	v_exp_f32_e32 v43, v43
	v_mul_f32_e32 v38, v39, v38
	v_add_f32_e32 v39, 1.0, v42
	v_rcp_f32_e32 v39, v39
	v_add_f32_e32 v42, 1.0, v43
	v_rcp_f32_e32 v42, v42
	v_pk_add_f32 v[36:37], v[68:69], v[36:37]
	v_mul_f32_e32 v35, v38, v35
	v_mul_f32_e32 v38, v40, v39
	v_mul_f32_e32 v36, v38, v36
	v_mul_f32_e32 v38, v41, v42
	v_mul_f32_e32 v37, v38, v37
	v_add_u32_e32 v38, 0xb0, v174
	v_cvt_pk_bf16_f32 v34, v34, v35
	v_cvt_pk_bf16_f32 v35, v36, v37
	v_mad_i64_i32 v[36:37], s[22:23], v38, s25, v[58:59]
	v_lshl_add_u64 v[36:37], v[36:37], 0, s[46:47]
	v_lshl_add_u64 v[36:37], v[36:37], 0, s[62:63]
	v_lshl_add_u64 v[82:83], v[36:37], 0, v[162:163]
	global_store_dwordx2 v[82:83], v[34:35], off
	ds_read_b128 v[46:49], v214 offset:16
	ds_read_b128 v[42:45], v214 offset:1040
	ds_read_b128 v[38:41], v214 offset:2064
	ds_read_b128 v[34:37], v214 offset:3088
	v_mov_b32_e32 v74, 0
	v_mov_b32_e32 v78, 0
	v_mov_b32_e32 v79, 0
	v_mov_b32_e32 v80, 0
	v_mov_b32_e32 v81, 0
	v_mov_b32_e32 v70, 0
	v_mov_b32_e32 v71, 0
	v_mov_b32_e32 v72, 0
	v_mov_b32_e32 v73, 0
	s_and_saveexec_b64 s[46:47], s[44:45]
	s_cbranch_execz .LBB0_730
	s_lshl_b32 s2, s97, 4
	v_add3_u32 v50, v213, v148, s2
	ds_read_b128 v[78:81], v50
	ds_read_b128 v[70:73], v50 offset:16

; __device__ __forceinline__ unsigned cvt_pk_bf16(float lo, float hi) { unsigned r; asm volatile("v_cvt_pk_bf16_f32 %0, %1, %2" : "=v"(r) : "v"(lo), "v"(hi)); return r; }
; DI float dpp_ror1(float x) { float r; asm volatile("s_nop 1\n\tv_mov_b32_dpp %0, %1 row_ror:1 row_mask:0xf bank_mask:0xf" : "=v"(r) : "v"(x)); return r; }
; DI float dpp_ror2(float x) { float r; asm volatile("s_nop 1\n\tv_mov_b32_dpp %0, %1 row_ror:2 row_mask:0xf bank_mask:0xf" : "=v"(r) : "v"(x)); return r; }
;     __device__ __forceinline__ void operator()(const f32x4 (&acc)[2][2][4][2], const Unit& u, int wr, int wc, int fr_in, int fq_in) const {
;     ...
;                     r1p[bj] = E1; r2p[bj] = (fr == 0) ? E0 : E1;
;                 }
; #pragma unroll
;                 for (int m = 0; m < 4; ++m) {
;                     f32x4 uu[2];
; #pragma unroll
;                     for (int bj = 0; bj < 2; ++bj) {
;                         const f32x4 cur = acc[ai][bj][m][n];
;                         f32x4 r1, r2;
; #pragma unroll
;                         for (int j = 0; j < 4; ++j) { r1[j] = dpp_ror1(cur[j]); r2[j] = dpp_ror2(cur[j]); }
;                         const f32x4 p1 = (fr >= 1) ? r1 : r1p[bj], p2 = (fr >= 2) ? r2 : r2p[bj];
;                         uu[bj] = w0[bj] * p2 + w1[bj] * p1 + w2[bj] * cur + bb[bj];
;                         r1p[bj] = r1; r2p[bj] = r2;
;                     }
;                     const int row = row0 + ai * HALF + m * 16;
;                     float a[4];
; #pragma unroll
;                     for (int j = 0; j < 4; ++j) { const float g = uu[0][j]; a[j] = g * __builtin_amdgcn_rcpf(1.f + __expf(-g)) * uu[1][j]; }
;                     u32x2 w; w.x = cvt_pk_bf16(a[0], a[1]); w.y = cvt_pk_bf16(a[2], a[3]);
;                     *(u32x2*)(ACT + (size_t)row * FFN + u.pn * HALF + wc * 32 + 8 * fq + 4 * n) = w;
.LBB0_732:
	s_or_b64 exec, exec, s[46:47]
	s_waitcnt lgkmcnt(0)
	v_cndmask_b32_e32 v79, v71, v79, vcc
	v_cndmask_b32_e32 v78, v70, v78, vcc
	v_cndmask_b32_e32 v81, v73, v81, vcc
	v_cndmask_b32_e32 v80, v72, v80, vcc
	v_cndmask_b32_e32 v86, v69, v77, vcc
	v_cndmask_b32_e32 v87, v68, v76, vcc
	v_mov_b32_dpp v88, v30 row_ror:1 row_mask:0xf bank_mask:0xf
	v_mov_b32_dpp v89, v30 row_ror:2 row_mask:0xf bank_mask:0xf
	v_mov_b32_dpp v90, v31 row_ror:1 row_mask:0xf bank_mask:0xf
	v_mov_b32_dpp v91, v31 row_ror:2 row_mask:0xf bank_mask:0xf
	v_cndmask_b32_e32 v84, v67, v75, vcc
	v_cndmask_b32_e64 v76, v78, v89, s[42:43]
	v_cndmask_b32_e64 v77, v79, v91, s[42:43]
	v_cndmask_b32_e32 v85, v66, v74, vcc
	v_mov_b32_dpp v92, v32 row_ror:1 row_mask:0xf bank_mask:0xf
	v_mov_b32_dpp v93, v32 row_ror:2 row_mask:0xf bank_mask:0xf
	v_mov_b32_dpp v94, v33 row_ror:1 row_mask:0xf bank_mask:0xf
	v_mov_b32_dpp v95, v33 row_ror:2 row_mask:0xf bank_mask:0xf
	v_cndmask_b32_e32 v70, v88, v70, vcc
	v_cndmask_b32_e32 v71, v90, v71, vcc
	v_cndmask_b32_e64 v74, v80, v93, s[42:43]
	v_cndmask_b32_e64 v75, v81, v95, s[42:43]
	v_pk_mul_f32 v[76:77], v[46:47], v[76:77]
	v_cndmask_b32_e32 v72, v92, v72, vcc
	v_cndmask_b32_e32 v73, v94, v73, vcc
	v_pk_mul_f32 v[74:75], v[48:49], v[74:75]
	v_pk_fma_f32 v[70:71], v[42:43], v[70:71], v[76:77]
	v_pk_fma_f32 v[72:73], v[44:45], v[72:73], v[74:75]
	v_pk_fma_f32 v[30:31], v[30:31], v[38:39], v[70:71]
	v_mov_b32_dpp v74, v26 row_ror:1 row_mask:0xf bank_mask:0xf
	v_mov_b32_dpp v75, v26 row_ror:2 row_mask:0xf bank_mask:0xf
	v_mov_b32_dpp v76, v27 row_ror:1 row_mask:0xf bank_mask:0xf
	v_mov_b32_dpp v77, v27 row_ror:2 row_mask:0xf bank_mask:0xf
	v_mov_b32_dpp v78, v28 row_ror:1 row_mask:0xf bank_mask:0xf
	v_mov_b32_dpp v79, v28 row_ror:2 row_mask:0xf bank_mask:0xf
	v_mov_b32_dpp v80, v29 row_ror:1 row_mask:0xf bank_mask:0xf
	v_mov_b32_dpp v81, v29 row_ror:2 row_mask:0xf bank_mask:0xf
	s_nop 0
	v_pk_add_f32 v[30:31], v[34:35], v[30:31]
	v_cndmask_b32_e64 v70, v87, v79, s[42:43]
	v_cndmask_b32_e64 v71, v86, v81, s[42:43]
	v_cndmask_b32_e32 v68, v78, v68, vcc
	v_cndmask_b32_e32 v69, v80, v69, vcc
	v_pk_mul_f32 v[70:71], v[64:65], v[70:71]
	v_pk_fma_f32 v[32:33], v[32:33], v[40:41], v[72:73]
	v_pk_fma_f32 v[68:69], v[60:61], v[68:69], v[70:71]
	v_mul_f32_e32 v70, 0xbfb8aa3b, v30
	v_exp_f32_e32 v70, v70
	v_cndmask_b32_e64 v72, v85, v75, s[42:43]
	v_cndmask_b32_e64 v73, v84, v77, s[42:43]
	v_cndmask_b32_e32 v66, v74, v66, vcc
	v_cndmask_b32_e32 v67, v76, v67, vcc
	v_pk_mul_f32 v[72:73], v[62:63], v[72:73]
	v_pk_add_f32 v[32:33], v[36:37], v[32:33]
	v_pk_fma_f32 v[66:67], v[58:59], v[66:67], v[72:73]
	v_pk_fma_f32 v[28:29], v[28:29], v[56:57], v[68:69]
	v_pk_fma_f32 v[26:27], v[26:27], v[54:55], v[66:67]
	v_add_f32_e32 v66, 1.0, v70
	v_rcp_f32_e32 v66, v66
	v_mul_f32_e32 v67, 0xbfb8aa3b, v31
	v_exp_f32_e32 v67, v67
	v_pk_add_f32 v[26:27], v[50:51], v[26:27]
	v_mul_f32_e32 v30, v30, v66
	v_mul_f32_e32 v26, v30, v26
	v_add_f32_e32 v30, 1.0, v67
	v_mul_f32_e32 v66, 0xbfb8aa3b, v32
	v_rcp_f32_e32 v30, v30
	v_exp_f32_e32 v66, v66
	v_mul_f32_e32 v67, 0xbfb8aa3b, v33
	v_exp_f32_e32 v67, v67
	v_mul_f32_e32 v30, v31, v30
	v_add_f32_e32 v31, 1.0, v66
	v_rcp_f32_e32 v31, v31
	v_add_f32_e32 v66, 1.0, v67
	v_rcp_f32_e32 v66, v66
	v_pk_add_f32 v[28:29], v[52:53], v[28:29]
	v_mul_f32_e32 v27, v30, v27
	v_mul_f32_e32 v30, v32, v31
	v_mul_f32_e32 v28, v30, v28
	v_mul_f32_e32 v30, v33, v66
	v_mul_f32_e32 v29, v30, v29
	v_cvt_pk_bf16_f32 v26, v26, v27
	v_cvt_pk_bf16_f32 v27, v28, v29
	global_store_dwordx2 v[98:99], v[26:27], off offset:8
	v_mov_b32_dpp v66, v22 row_ror:1 row_mask:0xf bank_mask:0xf
	v_mov_b32_dpp v67, v22 row_ror:2 row_mask:0xf bank_mask:0xf
	v_mov_b32_dpp v68, v23 row_ror:1 row_mask:0xf bank_mask:0xf
	v_mov_b32_dpp v69, v23 row_ror:2 row_mask:0xf bank_mask:0xf
	v_mov_b32_dpp v70, v24 row_ror:1 row_mask:0xf bank_mask:0xf
	v_mov_b32_dpp v71, v24 row_ror:2 row_mask:0xf bank_mask:0xf
	v_mov_b32_dpp v72, v25 row_ror:1 row_mask:0xf bank_mask:0xf
	s_nop 0
	v_cndmask_b32_e64 v32, v89, v67, s[42:43]
	v_cndmask_b32_e64 v33, v91, v69, s[42:43]
	v_mov_b32_dpp v73, v25 row_ror:2 row_mask:0xf bank_mask:0xf
	v_cndmask_b32_e32 v26, v66, v88, vcc
	v_cndmask_b32_e32 v27, v68, v90, vcc
	v_cndmask_b32_e64 v30, v93, v71, s[42:43]
	v_cndmask_b32_e64 v31, v95, v73, s[42:43]
	v_pk_mul_f32 v[32:33], v[46:47], v[32:33]
	v_cndmask_b32_e32 v28, v70, v92, vcc
	v_cndmask_b32_e32 v29, v72, v94, vcc
	v_pk_mul_f32 v[30:31], v[48:49], v[30:31]
	v_pk_fma_f32 v[26:27], v[42:43], v[26:27], v[32:33]
	v_pk_fma_f32 v[28:29], v[44:45], v[28:29], v[30:31]
	v_pk_fma_f32 v[22:23], v[22:23], v[38:39], v[26:27]
	v_mov_b32_dpp v84, v18 row_ror:1 row_mask:0xf bank_mask:0xf
	v_mov_b32_dpp v85, v18 row_ror:2 row_mask:0xf bank_mask:0xf
	v_mov_b32_dpp v86, v19 row_ror:1 row_mask:0xf bank_mask:0xf
	v_mov_b32_dpp v87, v19 row_ror:2 row_mask:0xf bank_mask:0xf
	v_mov_b32_dpp v88, v20 row_ror:1 row_mask:0xf bank_mask:0xf
	v_mov_b32_dpp v89, v20 row_ror:2 row_mask:0xf bank_mask:0xf
	v_mov_b32_dpp v90, v21 row_ror:1 row_mask:0xf bank_mask:0xf
	v_mov_b32_dpp v91, v21 row_ror:2 row_mask:0xf bank_mask:0xf
	v_pk_fma_f32 v[24:25], v[24:25], v[40:41], v[28:29]
	v_cndmask_b32_e64 v30, v79, v89, s[42:43]
	v_cndmask_b32_e64 v31, v81, v91, s[42:43]
	v_pk_add_f32 v[22:23], v[34:35], v[22:23]
	v_cndmask_b32_e32 v28, v88, v78, vcc
	v_cndmask_b32_e32 v29, v90, v80, vcc
	v_pk_mul_f32 v[30:31], v[64:65], v[30:31]
	v_cndmask_b32_e64 v32, v75, v85, s[42:43]
	v_pk_fma_f32 v[28:29], v[60:61], v[28:29], v[30:31]
	v_mul_f32_e32 v30, 0xbfb8aa3b, v22
	v_exp_f32_e32 v30, v30
	v_cndmask_b32_e64 v33, v77, v87, s[42:43]
; __device__ __forceinline__ unsigned cvt_pk_bf16(float lo, float hi) { unsigned r; asm volatile("v_cvt_pk_bf16_f32 %0, %1, %2" : "=v"(r) : "v"(lo), "v"(hi)); return r; }
; DI float dpp_ror1(float x) { float r; asm volatile("s_nop 1\n\tv_mov_b32_dpp %0, %1 row_ror:1 row_mask:0xf bank_mask:0xf" : "=v"(r) : "v"(x)); return r; }
; DI float dpp_ror2(float x) { float r; asm volatile("s_nop 1\n\tv_mov_b32_dpp %0, %1 row_ror:2 row_mask:0xf bank_mask:0xf" : "=v"(r) : "v"(x)); return r; }
;     __device__ __forceinline__ void operator()(const f32x4 (&acc)[2][2][4][2], const Unit& u, int wr, int wc, int fr_in, int fq_in) const {
;     ...
;                 for (int m = 0; m < 4; ++m) {
;                     f32x4 uu[2];
; #pragma unroll
;                     for (int bj = 0; bj < 2; ++bj) {
;                         const f32x4 cur = acc[ai][bj][m][n];
;                         f32x4 r1, r2;
; #pragma unroll
;                         for (int j = 0; j < 4; ++j) { r1[j] = dpp_ror1(cur[j]); r2[j] = dpp_ror2(cur[j]); }
;                         const f32x4 p1 = (fr >= 1) ? r1 : r1p[bj], p2 = (fr >= 2) ? r2 : r2p[bj];
;                         uu[bj] = w0[bj] * p2 + w1[bj] * p1 + w2[bj] * cur + bb[bj];
;                         r1p[bj] = r1; r2p[bj] = r2;
;                     }
;                     const int row = row0 + ai * HALF + m * 16;
;                     float a[4];
; #pragma unroll
;                     for (int j = 0; j < 4; ++j) { const float g = uu[0][j]; a[j] = g * __builtin_amdgcn_rcpf(1.f + __expf(-g)) * uu[1][j]; }
;                     u32x2 w; w.x = cvt_pk_bf16(a[0], a[1]); w.y = cvt_pk_bf16(a[2], a[3]);
;                     *(u32x2*)(ACT + (size_t)row * FFN + u.pn * HALF + wc * 32 + 8 * fq + 4 * n) = w;
	v_cndmask_b32_e32 v26, v84, v74, vcc
	v_cndmask_b32_e32 v27, v86, v76, vcc
	v_pk_mul_f32 v[32:33], v[62:63], v[32:33]
	v_pk_add_f32 v[24:25], v[36:37], v[24:25]
	v_pk_fma_f32 v[26:27], v[58:59], v[26:27], v[32:33]
	v_pk_fma_f32 v[20:21], v[20:21], v[56:57], v[28:29]
	v_pk_fma_f32 v[18:19], v[18:19], v[54:55], v[26:27]
	v_add_f32_e32 v26, 1.0, v30
	v_rcp_f32_e32 v26, v26
	v_mul_f32_e32 v27, 0xbfb8aa3b, v23
	v_exp_f32_e32 v27, v27
	v_pk_add_f32 v[18:19], v[50:51], v[18:19]
	v_mul_f32_e32 v22, v22, v26
	v_mul_f32_e32 v18, v22, v18
	v_add_f32_e32 v22, 1.0, v27
	v_mul_f32_e32 v26, 0xbfb8aa3b, v24
	v_rcp_f32_e32 v22, v22
	v_exp_f32_e32 v26, v26
	v_mul_f32_e32 v27, 0xbfb8aa3b, v25
	v_exp_f32_e32 v27, v27
	v_mul_f32_e32 v22, v23, v22
	v_add_f32_e32 v23, 1.0, v26
	v_rcp_f32_e32 v23, v23
	v_add_f32_e32 v26, 1.0, v27
	v_rcp_f32_e32 v26, v26
	v_pk_add_f32 v[20:21], v[52:53], v[20:21]
	v_mul_f32_e32 v19, v22, v19
	v_mul_f32_e32 v22, v24, v23
	v_mul_f32_e32 v20, v22, v20
	v_mul_f32_e32 v22, v25, v26
	v_mul_f32_e32 v21, v22, v21
	v_cvt_pk_bf16_f32 v18, v18, v19
	v_cvt_pk_bf16_f32 v19, v20, v21
	global_store_dwordx2 v[100:101], v[18:19], off offset:8
	v_mov_b32_dpp v26, v14 row_ror:1 row_mask:0xf bank_mask:0xf
	v_mov_b32_dpp v27, v14 row_ror:2 row_mask:0xf bank_mask:0xf
	v_mov_b32_dpp v28, v15 row_ror:1 row_mask:0xf bank_mask:0xf
	v_mov_b32_dpp v29, v15 row_ror:2 row_mask:0xf bank_mask:0xf
	v_mov_b32_dpp v30, v16 row_ror:1 row_mask:0xf bank_mask:0xf
	v_mov_b32_dpp v31, v16 row_ror:2 row_mask:0xf bank_mask:0xf
	v_mov_b32_dpp v32, v17 row_ror:1 row_mask:0xf bank_mask:0xf
	s_nop 0
	v_cndmask_b32_e64 v24, v67, v27, s[42:43]
	v_cndmask_b32_e64 v25, v69, v29, s[42:43]
	v_mov_b32_dpp v33, v17 row_ror:2 row_mask:0xf bank_mask:0xf
	v_cndmask_b32_e32 v18, v26, v66, vcc
	v_cndmask_b32_e32 v19, v28, v68, vcc
	v_cndmask_b32_e64 v22, v71, v31, s[42:43]
	v_cndmask_b32_e64 v23, v73, v33, s[42:43]
	v_pk_mul_f32 v[24:25], v[46:47], v[24:25]
	v_cndmask_b32_e32 v20, v30, v70, vcc
	v_cndmask_b32_e32 v21, v32, v72, vcc
	v_pk_mul_f32 v[22:23], v[48:49], v[22:23]
	v_pk_fma_f32 v[18:19], v[42:43], v[18:19], v[24:25]
	v_pk_fma_f32 v[20:21], v[44:45], v[20:21], v[22:23]
	v_pk_fma_f32 v[14:15], v[14:15], v[38:39], v[18:19]
	v_mov_b32_dpp v66, v10 row_ror:1 row_mask:0xf bank_mask:0xf
	v_mov_b32_dpp v67, v10 row_ror:2 row_mask:0xf bank_mask:0xf
	v_mov_b32_dpp v68, v11 row_ror:1 row_mask:0xf bank_mask:0xf
	v_mov_b32_dpp v69, v11 row_ror:2 row_mask:0xf bank_mask:0xf
	v_mov_b32_dpp v70, v12 row_ror:1 row_mask:0xf bank_mask:0xf
	v_mov_b32_dpp v71, v12 row_ror:2 row_mask:0xf bank_mask:0xf
	v_mov_b32_dpp v72, v13 row_ror:1 row_mask:0xf bank_mask:0xf
	v_mov_b32_dpp v73, v13 row_ror:2 row_mask:0xf bank_mask:0xf
	v_pk_fma_f32 v[16:17], v[16:17], v[40:41], v[20:21]
	v_cndmask_b32_e64 v22, v89, v71, s[42:43]
	v_cndmask_b32_e64 v23, v91, v73, s[42:43]
	v_pk_add_f32 v[14:15], v[34:35], v[14:15]
	v_cndmask_b32_e32 v20, v70, v88, vcc
	v_cndmask_b32_e32 v21, v72, v90, vcc
	v_pk_mul_f32 v[22:23], v[64:65], v[22:23]
	v_cndmask_b32_e64 v24, v85, v67, s[42:43]
	v_pk_fma_f32 v[20:21], v[60:61], v[20:21], v[22:23]
	v_mul_f32_e32 v22, 0xbfb8aa3b, v14
	v_exp_f32_e32 v22, v22
	v_cndmask_b32_e64 v25, v87, v69, s[42:43]
	v_cndmask_b32_e32 v18, v66, v84, vcc
	v_cndmask_b32_e32 v19, v68, v86, vcc
	v_pk_mul_f32 v[24:25], v[62:63], v[24:25]
	v_pk_add_f32 v[16:17], v[36:37], v[16:17]
	v_pk_fma_f32 v[18:19], v[58:59], v[18:19], v[24:25]
	v_pk_fma_f32 v[12:13], v[12:13], v[56:57], v[20:21]
	v_pk_fma_f32 v[10:11], v[10:11], v[54:55], v[18:19]
	v_add_f32_e32 v18, 1.0, v22
	v_rcp_f32_e32 v18, v18
	v_mul_f32_e32 v19, 0xbfb8aa3b, v15
	v_exp_f32_e32 v19, v19
	v_pk_add_f32 v[10:11], v[50:51], v[10:11]
	v_mul_f32_e32 v14, v14, v18
	v_mul_f32_e32 v10, v14, v10
	v_add_f32_e32 v14, 1.0, v19
	v_mul_f32_e32 v18, 0xbfb8aa3b, v16
	v_rcp_f32_e32 v14, v14
	v_exp_f32_e32 v18, v18
	v_mul_f32_e32 v19, 0xbfb8aa3b, v17
	v_exp_f32_e32 v19, v19
	v_mul_f32_e32 v14, v15, v14
	v_add_f32_e32 v15, 1.0, v18
	v_rcp_f32_e32 v15, v15
	v_add_f32_e32 v18, 1.0, v19
	v_rcp_f32_e32 v18, v18
	v_pk_add_f32 v[12:13], v[52:53], v[12:13]
	v_mul_f32_e32 v11, v14, v11
	v_mul_f32_e32 v14, v16, v15
	v_mul_f32_e32 v12, v14, v12
	v_mul_f32_e32 v14, v17, v18
	v_mul_f32_e32 v13, v14, v13
	v_cvt_pk_bf16_f32 v10, v10, v11
	v_cvt_pk_bf16_f32 v11, v12, v13
	global_store_dwordx2 v[102:103], v[10:11], off offset:8
	v_mov_b32_dpp v12, v6 row_ror:1 row_mask:0xf bank_mask:0xf
	v_mov_b32_dpp v14, v6 row_ror:2 row_mask:0xf bank_mask:0xf
	v_mov_b32_dpp v13, v7 row_ror:1 row_mask:0xf bank_mask:0xf
; #define PG8_LAS __attribute__((address_space(3)))
; __device__ __forceinline__ unsigned cvt_pk_bf16(float lo, float hi) { unsigned r; asm volatile("v_cvt_pk_bf16_f32 %0, %1, %2" : "=v"(r) : "v"(lo), "v"(hi)); return r; }
; DI int opaque_lane() { int l; asm volatile("v_mbcnt_lo_u32_b32 %0, -1, 0\n\tv_mbcnt_hi_u32_b32 %0, -1, %0" : "=v"(l)); return l; }
;     __device__ __forceinline__ void pre(const Unit& u, int wr, int wc) const {
;         const int lane_p = opaque_lane(); const int wv = wr * 4 + wc, t = wv * 64 + lane_p;
;         PG8_LAS unsigned char* dst = cwl3 + par_w * 6144 + wv * 256;
; #pragma unroll
;         for (int i = 0; i < 2; ++i) { const int idx = t + 512 * i, k = idx >> 8, c = idx & 255;
;             const int oc = (c < 128) ? (u.pn * HALF + c) : (FFN + u.pn * HALF + c - 128);
;             const float* src = (k < 3) ? (cw + (size_t)k * NUP + oc) : (cb + oc);
;             __builtin_amdgcn_global_load_lds((const unsigned*)src, (PG8_LAS unsigned*)(dst + i * 2048), 4, 0, 0); }
;         par_w ^= 1;
;     __device__ __forceinline__ void operator()(const f32x4 (&acc)[2][2][4][2], const Unit& u, int wr, int wc, int fr_in, int fq_in) const {
;     ...
;                 for (int m = 0; m < 4; ++m) {
;                     f32x4 uu[2];
; #pragma unroll
;                     for (int bj = 0; bj < 2; ++bj) {
;                         const f32x4 cur = acc[ai][bj][m][n];
;                         f32x4 r1, r2;
; #pragma unroll
;                         for (int j = 0; j < 4; ++j) { r1[j] = dpp_ror1(cur[j]); r2[j] = dpp_ror2(cur[j]); }
;                         const f32x4 p1 = (fr >= 1) ? r1 : r1p[bj], p2 = (fr >= 2) ? r2 : r2p[bj];
;                         uu[bj] = w0[bj] * p2 + w1[bj] * p1 + w2[bj] * cur + bb[bj];
;                         r1p[bj] = r1; r2p[bj] = r2;
;                     }
;                     const int row = row0 + ai * HALF + m * 16;
;                     float a[4];
; #pragma unroll
;                     for (int j = 0; j < 4; ++j) { const float g = uu[0][j]; a[j] = g * __builtin_amdgcn_rcpf(1.f + __expf(-g)) * uu[1][j]; }
;                     u32x2 w; w.x = cvt_pk_bf16(a[0], a[1]); w.y = cvt_pk_bf16(a[2], a[3]);
;                     *(u32x2*)(ACT + (size_t)row * FFN + u.pn * HALF + wc * 32 + 8 * fq + 4 * n) = w;
	v_mov_b32_dpp v15, v7 row_ror:2 row_mask:0xf bank_mask:0xf
	v_mov_b32_dpp v10, v8 row_ror:1 row_mask:0xf bank_mask:0xf
	v_mov_b32_dpp v16, v8 row_ror:2 row_mask:0xf bank_mask:0xf
	s_nop 0
	v_cndmask_b32_e32 v12, v12, v26, vcc
	v_cndmask_b32_e64 v14, v27, v14, s[42:43]
	v_cndmask_b32_e64 v15, v29, v15, s[42:43]
	v_cndmask_b32_e32 v13, v13, v28, vcc
	v_pk_mul_f32 v[14:15], v[46:47], v[14:15]
	v_mov_b32_dpp v11, v9 row_ror:1 row_mask:0xf bank_mask:0xf
	v_mov_b32_dpp v17, v9 row_ror:2 row_mask:0xf bank_mask:0xf
	v_cndmask_b32_e64 v16, v31, v16, s[42:43]
	v_pk_fma_f32 v[12:13], v[42:43], v[12:13], v[14:15]
	v_cndmask_b32_e64 v17, v33, v17, s[42:43]
	v_pk_fma_f32 v[6:7], v[6:7], v[38:39], v[12:13]
	v_cndmask_b32_e32 v10, v10, v30, vcc
	v_pk_add_f32 v[6:7], v[34:35], v[6:7]
	v_cndmask_b32_e32 v11, v11, v32, vcc
	v_mul_f32_e32 v14, 0xbfb8aa3b, v6
	v_mov_b32_dpp v18, v2 row_ror:1 row_mask:0xf bank_mask:0xf
	v_mov_b32_dpp v24, v2 row_ror:2 row_mask:0xf bank_mask:0xf
	v_mov_b32_dpp v19, v3 row_ror:1 row_mask:0xf bank_mask:0xf
	v_mov_b32_dpp v25, v3 row_ror:2 row_mask:0xf bank_mask:0xf
	v_pk_mul_f32 v[16:17], v[48:49], v[16:17]
	v_exp_f32_e32 v14, v14
	v_cndmask_b32_e64 v24, v67, v24, s[42:43]
	v_cndmask_b32_e64 v25, v69, v25, s[42:43]
	v_pk_fma_f32 v[10:11], v[44:45], v[10:11], v[16:17]
	v_cndmask_b32_e32 v18, v18, v66, vcc
	v_cndmask_b32_e32 v19, v19, v68, vcc
	v_pk_fma_f32 v[8:9], v[8:9], v[40:41], v[10:11]
	v_pk_mul_f32 v[10:11], v[62:63], v[24:25]
	v_pk_add_f32 v[8:9], v[36:37], v[8:9]
	v_pk_fma_f32 v[10:11], v[58:59], v[18:19], v[10:11]
	v_mov_b32_dpp v20, v4 row_ror:1 row_mask:0xf bank_mask:0xf
	v_mov_b32_dpp v22, v4 row_ror:2 row_mask:0xf bank_mask:0xf
	v_mov_b32_dpp v21, v5 row_ror:1 row_mask:0xf bank_mask:0xf
	v_mov_b32_dpp v23, v5 row_ror:2 row_mask:0xf bank_mask:0xf
	s_nop 0
	v_pk_fma_f32 v[2:3], v[2:3], v[54:55], v[10:11]
	v_add_f32_e32 v10, 1.0, v14
	v_rcp_f32_e32 v10, v10
	v_mul_f32_e32 v11, 0xbfb8aa3b, v7
	v_exp_f32_e32 v11, v11
	v_pk_add_f32 v[2:3], v[50:51], v[2:3]
	v_mul_f32_e32 v6, v6, v10
	v_mul_f32_e32 v2, v6, v2
	v_add_f32_e32 v6, 1.0, v11
	v_mul_f32_e32 v10, 0xbfb8aa3b, v8
	v_rcp_f32_e32 v6, v6
	v_exp_f32_e32 v10, v10
	v_mul_f32_e32 v11, 0xbfb8aa3b, v9
	v_exp_f32_e32 v11, v11
	v_mul_f32_e32 v6, v7, v6
	v_add_f32_e32 v7, 1.0, v10
	v_cndmask_b32_e64 v22, v71, v22, s[42:43]
	v_cndmask_b32_e64 v23, v73, v23, s[42:43]
	v_rcp_f32_e32 v7, v7
	v_add_f32_e32 v10, 1.0, v11
	v_cndmask_b32_e32 v20, v20, v70, vcc
	v_cndmask_b32_e32 v21, v21, v72, vcc
	v_pk_mul_f32 v[12:13], v[64:65], v[22:23]
	v_rcp_f32_e32 v10, v10
	v_pk_fma_f32 v[12:13], v[60:61], v[20:21], v[12:13]
	v_mul_f32_e32 v3, v6, v3
	v_pk_fma_f32 v[4:5], v[4:5], v[56:57], v[12:13]
	v_mul_f32_e32 v6, v8, v7
	v_pk_add_f32 v[4:5], v[52:53], v[4:5]
	s_andn2_b64 vcc, exec, s[40:41]
	v_mul_f32_e32 v4, v6, v4
	v_mul_f32_e32 v6, v9, v10
	s_mov_b64 s[40:41], -1
	v_mul_f32_e32 v5, v6, v5
	v_cvt_pk_bf16_f32 v2, v2, v3
	v_cvt_pk_bf16_f32 v3, v4, v5
	global_store_dwordx2 v[82:83], v[2:3], off offset:8
	s_cbranch_vccnz .LBB0_701
	v_readlane_b32 s2, v243, 48
	v_mbcnt_lo_u32_b32 v2, -1, 0
	v_mbcnt_hi_u32_b32 v2, -1, v2
	v_mov_b64_e32 v[4:5], s[56:57]
	s_nop 0
	v_add_u32_e32 v6, s2, v2
	v_ashrrev_i32_e32 v2, 8, v6
	v_cmp_gt_i32_e32 vcc, 3, v2
	s_and_saveexec_b64 s[40:41], vcc
	v_mul_hi_i32_i24_e32 v3, 0x5800, v2
	v_mul_i32_i24_e32 v2, 0x5800, v2
	v_lshl_add_u64 v[4:5], s[54:55], 0, v[2:3]
	s_or_b64 exec, exec, s[40:41]
	s_lshl_b32 s8, s58, 7
	v_or_b32_sdwa v2, v6, s8 dst_sel:DWORD dst_unused:UNUSED_PAD src0_sel:BYTE_0 src1_sel:DWORD
	s_addk_i32 s8, 0xa80
	v_add_u32_sdwa v3, s8, v6 dst_sel:DWORD dst_unused:UNUSED_PAD src0_sel:DWORD src1_sel:BYTE_0
	s_movk_i32 s8, 0x80
	v_cmp_lt_u32_sdwa vcc, v6, s8 src0_sel:BYTE_0 src1_sel:DWORD
	s_mul_i32 s2, s4, 0x1800
	v_readlane_b32 s8, v239, 22
	v_cndmask_b32_e32 v2, v3, v2, vcc
	v_ashrrev_i32_e32 v3, 31, v2
	s_add_i32 s2, s8, s2
	v_lshl_add_u64 v[4:5], v[2:3], 2, v[4:5]
	s_mov_b32 m0, s2
	s_nop 0
	global_load_lds_dword v[4:5], off
	v_add_u32_e32 v4, 0x200, v6
	v_ashrrev_i32_e32 v6, 8, v4
	v_cmp_gt_i32_e32 vcc, 3, v6
	v_mov_b64_e32 v[4:5], s[56:57]
	s_and_saveexec_b64 s[40:41], vcc
	v_mul_hi_i32_i24_e32 v5, 0x5800, v6
	v_mul_i32_i24_e32 v4, 0x5800, v6
	v_lshl_add_u64 v[4:5], s[54:55], 0, v[4:5]
	s_or_b64 exec, exec, s[40:41]
	v_lshl_add_u64 v[2:3], v[2:3], 2, v[4:5]
	s_add_i32 m0, s2, 0x800
	v_readlane_b32 s8, v239, 42
	global_load_lds_dword v[2:3], off
	v_readlane_b32 s9, v239, 43
	s_and_b64 vcc, exec, s[8:9]
	s_cbranch_vccnz .LBB0_700
	s_barrier
	s_branch .LBB0_700

; __global__ void __launch_bounds__(512, 2) hybrid_fwd(Params P) {
	.amdhsa_kernel _Z10hybrid_fwd6Params
		.amdhsa_group_segment_fixed_size 0
		.amdhsa_private_segment_fixed_size 0
		.amdhsa_kernarg_size 456
		.amdhsa_user_sgpr_count 2
		.amdhsa_user_sgpr_dispatch_ptr 0
		.amdhsa_user_sgpr_queue_ptr 0
		.amdhsa_user_sgpr_kernarg_segment_ptr 1
		.amdhsa_user_sgpr_dispatch_id 0
		.amdhsa_user_sgpr_kernarg_preload_length 0
		.amdhsa_user_sgpr_kernarg_preload_offset 0
		.amdhsa_user_sgpr_private_segment_size 0
		.amdhsa_uses_dynamic_stack 0
		.amdhsa_enable_private_segment 0
		.amdhsa_system_sgpr_workgroup_id_x 1
		.amdhsa_system_sgpr_workgroup_id_y 0
		.amdhsa_system_sgpr_workgroup_id_z 0
		.amdhsa_system_sgpr_workgroup_info 0
		.amdhsa_system_vgpr_workitem_id 2
		.amdhsa_next_free_vgpr 256
		.amdhsa_next_free_sgpr 100
		.amdhsa_accum_offset 256
		.amdhsa_reserve_vcc 1
		.amdhsa_float_round_mode_32 0
		.amdhsa_float_round_mode_16_64 0
		.amdhsa_float_denorm_mode_32 3
		.amdhsa_float_denorm_mode_16_64 3
		.amdhsa_dx10_clamp 1
		.amdhsa_ieee_mode 1
		.amdhsa_fp16_overflow 0
		.amdhsa_tg_split 0
		.amdhsa_exception_fp_ieee_invalid_op 0
		.amdhsa_exception_fp_denorm_src 0
		.amdhsa_exception_fp_ieee_div_zero 0
		.amdhsa_exception_fp_ieee_overflow 0
		.amdhsa_exception_fp_ieee_underflow 0
		.amdhsa_exception_fp_ieee_inexact 0
		.amdhsa_exception_int_div_zero 0
	.end_amdhsa_kernel

; __global__ void __launch_bounds__(512, 2) hybrid_fwd(Params P) {
amdhsa.kernels:
  - .agpr_count:     0
    .args:
      - .offset:         0
        .size:           200
        .value_kind:     by_value
      - .offset:         200
        .size:           4
        .value_kind:     hidden_block_count_x
      - .offset:         204
        .size:           4
        .value_kind:     hidden_block_count_y
      - .offset:         208
        .size:           4
        .value_kind:     hidden_block_count_z
      - .offset:         212
        .size:           2
        .value_kind:     hidden_group_size_x
      - .offset:         214
        .size:           2
        .value_kind:     hidden_group_size_y
      - .offset:         216
        .size:           2
        .value_kind:     hidden_group_size_z
      - .offset:         218
        .size:           2
        .value_kind:     hidden_remainder_x
      - .offset:         220
        .size:           2
        .value_kind:     hidden_remainder_y
      - .offset:         222
        .size:           2
        .value_kind:     hidden_remainder_z
      - .offset:         240
        .size:           8
        .value_kind:     hidden_global_offset_x
      - .offset:         248
        .size:           8
        .value_kind:     hidden_global_offset_y
      - .offset:         256
        .size:           8
        .value_kind:     hidden_global_offset_z
      - .offset:         264
        .size:           2
        .value_kind:     hidden_grid_dims
      - .offset:         288
        .size:           8
        .value_kind:     hidden_multigrid_sync_arg
      - .offset:         320
        .size:           4
        .value_kind:     hidden_dynamic_lds_size
    .group_segment_fixed_size: 0
    .kernarg_segment_align: 8
    .kernarg_segment_size: 456
    .language:       OpenCL C
    .language_version:
      - 2
      - 0
    .max_flat_workgroup_size: 512
    .name:           _Z10hybrid_fwd6Params
    .private_segment_fixed_size: 0
    .sgpr_count:     106
    .sgpr_spill_count: 332
    .symbol:         _Z10hybrid_fwd6Params.kd
    .uniform_work_group_size: 1
    .uses_dynamic_stack: false
    .vgpr_count:     256
    .vgpr_spill_count: 0
    .wavefront_size: 64
